# lever 1: MODE-2 epilogues (Wo L0/L1, down) progressive counted waits on the first residual batch: vmcnt(6) per section instead of one vmcnt(0)
# baseline (speedup 1.0000x reference)
;     __device__ __forceinline__ void operator()(const f32x4 (&acc)[2][2][4][2], const Unit& u, int ui, int wr, int wc, int fr, int fq) const {
;     ...
;         if (FOLD) { const PG8_LAS int* sl = (const PG8_LAS int*)(tb + 16384); pslot = sl[ui] * 256; const int cslot = sl[16 + ui] * 256 + wc * 32 + 8 * fq;
;             const PG8_LAS float* csl = (const PG8_LAS float*)(tb + 8192); const PG8_LAS float* bwl = (const PG8_LAS float*)(tb + 12288);
; #pragma unroll
;             for (int bj = 0; bj < 2; ++bj)
; #pragma unroll
;                 for (int n = 0; n < 2; ++n) { cv[bj][n] = *(const PG8_LAS f32x4*)(csl + cslot + bj * HALF + 4 * n); bv[bj][n] = *(const PG8_LAS f32x4*)(bwl + cslot + bj * HALF + 4 * n); } }
; #pragma unroll
;         for (int ai = 0; ai < 2; ++ai) {
;         bf16x8 rr[4][2];
;         if (MODE == 2) {
; #pragma unroll
;             for (int m = 0; m < 4; ++m)
; #pragma unroll
;                 for (int bj = 0; bj < 2; ++bj) rr[m][bj] = *(const bf16x8*)(R + (size_t)(row0 + ai * HALF + m * 16) * ldc + col0 + bj * HALF);
;             __builtin_amdgcn_sched_barrier(0); }
; #pragma unroll
;             for (int m = 0; m < 4; ++m) { const int row = row0 + ai * HALF + m * 16; const size_t off = (size_t)row * ldc + col0;
;                 float mu = 0.f, rs = 1.f; if (FOLD) { const f32x2_t ms = ((const PG8_LAS f32x2_t*)tb)[pslot + ai * HALF + wr * 64 + m * 16 + fr]; mu = ms.x; rs = ms.y; }
;                 float ssum = 0.f, ssq = 0.f;
; #pragma unroll
;                 for (int bj = 0; bj < 2; ++bj) { f32x4 v0 = acc[ai][bj][m][0], v1 = acc[ai][bj][m][1];
;                     if (FOLD && MODE != 2) { v0 = (v0 - mu * cv[bj][0]) * rs + bv[bj][0]; v1 = (v1 - mu * cv[bj][1]) * rs + bv[bj][1]; }
;                     if (MODE == 0) { v0 = v0 * sc; v1 = v1 * sc; }
;                     if (MODE == 1) { v0 = __builtin_elementwise_max(v0, (f32x4){0.f, 0.f, 0.f, 0.f}); v1 = __builtin_elementwise_max(v1, (f32x4){0.f, 0.f, 0.f, 0.f}); v0 = v0 * v0; v1 = v1 * v1; }
;                     if (MODE == 2) { const bf16x8 r = rr[m][bj];
;                         f32x4 h0 = (f32x4){(float)r[0], (float)r[1], (float)r[2], (float)r[3]}, h1 = (f32x4){(float)r[4], (float)r[5], (float)r[6], (float)r[7]};
;                         if (FOLD) { h0 = (h0 - mu) * rs * cv[bj][0] + bv[bj][0]; h1 = (h1 - mu) * rs * cv[bj][1] + bv[bj][1]; }
.LBB0_787:
	v_lshl_or_b32 v66, s20, 8, v224
	v_lshl_add_u32 v202, s27, 8, v222
	v_ashrrev_i32_e32 v67, 31, v66
	v_readlane_b32 s12, v254, 41
	v_lshlrev_b64 v[200:201], 1, v[66:67]
	v_readlane_b32 s13, v254, 42
	v_ashrrev_i32_e32 v203, 31, v202
	v_lshlrev_b64 v[230:231], 11, v[202:203]
	v_lshl_add_u64 v[204:205], s[12:13], 0, v[200:201]
	v_or_b32_e32 v220, 16, v202
	v_lshl_add_u64 v[66:67], v[204:205], 0, v[230:231]
	v_ashrrev_i32_e32 v221, 31, v220
	global_load_dwordx4 v[208:211], v[66:67], off
	global_load_dwordx4 v[212:215], v[66:67], off offset:256
	v_lshlrev_b64 v[66:67], 11, v[220:221]
	v_or_b32_e32 v218, 32, v202
	v_lshl_add_u64 v[66:67], v[204:205], 0, v[66:67]
	v_ashrrev_i32_e32 v219, 31, v218
	global_load_dwordx4 v[186:189], v[66:67], off
	global_load_dwordx4 v[182:185], v[66:67], off offset:256
	v_lshlrev_b64 v[66:67], 11, v[218:219]
	v_or_b32_e32 v206, 48, v202
	v_lshl_add_u64 v[66:67], v[204:205], 0, v[66:67]
	v_ashrrev_i32_e32 v207, 31, v206
	global_load_dwordx4 v[178:181], v[66:67], off
	global_load_dwordx4 v[174:177], v[66:67], off offset:256
	v_lshlrev_b64 v[66:67], 11, v[206:207]
	v_lshl_add_u64 v[66:67], v[204:205], 0, v[66:67]
	global_load_dwordx4 v[170:173], v[66:67], off
	global_load_dwordx4 v[158:161], v[66:67], off offset:256
	s_lshl_b32 s12, s26, 2
	s_add_i32 s12, s12, 0
	s_add_i32 s12, s12, 0x24000
	v_mov_b32_e32 v1, s12
	ds_read2_b32 v[228:229], v1 offset1:16
	v_lshlrev_b32_e32 v1, 2, v224
	v_xor_b32_e32 v227, 16, v237
	s_lshl_b32 s16, s20, 2
	v_lshl_add_u64 v[200:201], s[56:57], 0, v[200:201]
	s_waitcnt lgkmcnt(0)
	v_lshl_or_b32 v1, v229, 10, v1
	v_add_u32_e32 v1, 0, v1
	v_add_u32_e32 v66, 0x22000, v1
	v_add_u32_e32 v1, 0x23000, v1
	ds_read_b128 v[94:97], v66
	ds_read_b128 v[86:89], v66 offset:16
	ds_read_b128 v[98:101], v1
	ds_read_b128 v[90:93], v1 offset:16
	ds_read_b128 v[78:81], v66 offset:512
	ds_read_b128 v[66:69], v66 offset:528
	ds_read_b128 v[82:85], v1 offset:512
	ds_read_b128 v[74:77], v1 offset:528
	v_lshlrev_b32_e32 v1, 11, v228
	v_and_b32_e32 v228, 64, v237
	v_add_u32_e32 v229, 64, v228
	v_cmp_lt_i32_e32 vcc, v227, v229
	s_ashr_i32 s17, s16, 31
	s_nop 0
	v_cndmask_b32_e32 v227, v237, v227, vcc
	v_lshlrev_b32_e32 v228, 2, v227
	v_xor_b32_e32 v227, 32, v237
	v_cmp_lt_i32_e32 vcc, v227, v229
	s_nop 1
	v_cndmask_b32_e32 v227, v237, v227, vcc
	v_lshlrev_b32_e32 v227, 2, v227
	v_add_u32_e32 v229, v225, v1
	ds_read_b64 v[232:233], v229
	s_waitcnt vmcnt(6)
	v_cvt_f32_f16_sdwa v1, v208 dst_sel:DWORD dst_unused:UNUSED_PAD src0_sel:WORD_1
	v_cvt_f32_f16_e32 v208, v208
	v_cvt_f32_f16_sdwa v238, v209 dst_sel:DWORD dst_unused:UNUSED_PAD src0_sel:WORD_1
	v_cvt_f32_f16_e32 v239, v209
	v_cvt_f32_f16_sdwa v240, v210 dst_sel:DWORD dst_unused:UNUSED_PAD src0_sel:WORD_1
	v_cvt_f32_f16_e32 v241, v210
	v_cvt_f32_f16_sdwa v242, v211 dst_sel:DWORD dst_unused:UNUSED_PAD src0_sel:WORD_1
	v_cvt_f32_f16_e32 v243, v211
	s_waitcnt lgkmcnt(0)
	v_sub_f32_e32 v208, v208, v232
	v_sub_f32_e32 v209, v1, v232
	v_sub_f32_e32 v210, v239, v232
	v_sub_f32_e32 v211, v238, v232
	v_pk_mul_f32 v[210:211], v[232:233], v[210:211] op_sel:[1,0]
	v_pk_mul_f32 v[208:209], v[232:233], v[208:209] op_sel:[1,0]
	v_sub_f32_e32 v238, v241, v232
	v_sub_f32_e32 v239, v240, v232
	v_sub_f32_e32 v240, v243, v232
	v_sub_f32_e32 v241, v242, v232
	v_pk_fma_f32 v[208:209], v[94:95], v[208:209], v[98:99]
	v_pk_fma_f32 v[210:211], v[96:97], v[210:211], v[100:101]
	v_pk_mul_f32 v[240:241], v[232:233], v[240:241] op_sel:[1,0]
	v_pk_mul_f32 v[238:239], v[232:233], v[238:239] op_sel:[1,0]
	v_pk_fma_f32 v[240:241], v[88:89], v[240:241], v[92:93]
	v_pk_fma_f32 v[238:239], v[86:87], v[238:239], v[90:91]
	v_pk_fma_f32 v[168:169], v[210:211], s[18:19], v[168:169] op_sel_hi:[1,0,1]
	v_pk_fma_f32 v[166:167], v[208:209], s[18:19], v[166:167] op_sel_hi:[1,0,1]
	v_pk_fma_f32 v[208:209], v[240:241], s[18:19], v[164:165] op_sel_hi:[1,0,1]
	v_pk_fma_f32 v[164:165], v[238:239], s[18:19], v[162:163] op_sel_hi:[1,0,1]
	v_pk_mov_b32 v[162:163], v[166:167], v[168:169] op_sel:[1,0]
	v_mov_b32_e32 v210, v166
	v_mov_b32_e32 v211, v169
	v_pk_add_f32 v[210:211], v[162:163], v[210:211]
	v_pk_mul_f32 v[162:163], v[168:169], v[168:169]
	v_pk_mul_f32 v[240:241], v[166:167], v[166:167]
	v_lshl_add_u64 v[230:231], v[200:201], 0, v[230:231]
	v_pk_mov_b32 v[242:243], v[240:241], v[162:163] op_sel:[1,0]
	v_mov_b32_e32 v241, v163
	v_pk_add_f32 v[162:163], v[242:243], v[240:241]
	v_add_f32_e32 v238, v164, v165
	v_pk_add_f32 v[240:241], v[162:163], v[162:163] op_sel_hi:[0,1]
	v_mul_f32_e32 v162, v164, v164
	v_pk_fma_f32 v[242:243], v[164:165], v[164:165], v[162:163] op_sel_hi:[1,1,0]
	v_cvt_pk_f16_f32 v162, v166, v167
	v_cvt_pk_f16_f32 v163, v168, v169
	v_cvt_pk_f16_f32 v164, v164, v165
	v_cvt_pk_f16_f32 v165, v208, v209
	global_store_dwordx4 v[230:231], v[162:165], off
	v_cvt_f32_f16_sdwa v167, v214 dst_sel:DWORD dst_unused:UNUSED_PAD src0_sel:WORD_1
	v_cvt_f32_f16_e32 v166, v214
	v_cvt_f32_f16_sdwa v163, v212 dst_sel:DWORD dst_unused:UNUSED_PAD src0_sel:WORD_1
	v_cvt_f32_f16_e32 v162, v212
	v_cvt_f32_f16_sdwa v165, v213 dst_sel:DWORD dst_unused:UNUSED_PAD src0_sel:WORD_1
	v_cvt_f32_f16_e32 v164, v213
	v_cvt_f32_f16_sdwa v169, v215 dst_sel:DWORD dst_unused:UNUSED_PAD src0_sel:WORD_1
	v_cvt_f32_f16_e32 v168, v215
	v_sub_f32_e32 v162, v162, v232
	v_sub_f32_e32 v163, v163, v232
	v_sub_f32_e32 v164, v164, v232
	v_sub_f32_e32 v165, v165, v232
	v_pk_mul_f32 v[164:165], v[232:233], v[164:165] op_sel:[1,0]
	v_pk_mul_f32 v[162:163], v[232:233], v[162:163] op_sel:[1,0]
	v_sub_f32_e32 v166, v166, v232
	v_sub_f32_e32 v167, v167, v232
	v_sub_f32_e32 v168, v168, v232
	v_sub_f32_e32 v169, v169, v232
; #define PG8_LAS __attribute__((address_space(3)))
;     __device__ __forceinline__ void operator()(const f32x4 (&acc)[2][2][4][2], const Unit& u, int ui, int wr, int wc, int fr, int fq) const {
;     ...
;             for (int m = 0; m < 4; ++m) { const int row = row0 + ai * HALF + m * 16; const size_t off = (size_t)row * ldc + col0;
;                 float mu = 0.f, rs = 1.f; if (FOLD) { const f32x2_t ms = ((const PG8_LAS f32x2_t*)tb)[pslot + ai * HALF + wr * 64 + m * 16 + fr]; mu = ms.x; rs = ms.y; }
;                 float ssum = 0.f, ssq = 0.f;
; #pragma unroll
;                 for (int bj = 0; bj < 2; ++bj) { f32x4 v0 = acc[ai][bj][m][0], v1 = acc[ai][bj][m][1];
;                     if (FOLD && MODE != 2) { v0 = (v0 - mu * cv[bj][0]) * rs + bv[bj][0]; v1 = (v1 - mu * cv[bj][1]) * rs + bv[bj][1]; }
;                     if (MODE == 0) { v0 = v0 * sc; v1 = v1 * sc; }
;                     if (MODE == 1) { v0 = __builtin_elementwise_max(v0, (f32x4){0.f, 0.f, 0.f, 0.f}); v1 = __builtin_elementwise_max(v1, (f32x4){0.f, 0.f, 0.f, 0.f}); v0 = v0 * v0; v1 = v1 * v1; }
;                     if (MODE == 2) { const bf16x8 r = rr[m][bj];
;                         f32x4 h0 = (f32x4){(float)r[0], (float)r[1], (float)r[2], (float)r[3]}, h1 = (f32x4){(float)r[4], (float)r[5], (float)r[6], (float)r[7]};
;                         if (FOLD) { h0 = (h0 - mu) * rs * cv[bj][0] + bv[bj][0]; h1 = (h1 - mu) * rs * cv[bj][1] + bv[bj][1]; }
;                         v0 = v0 + alpha * h0; v1 = v1 + alpha * h1;
;                         ssum += (v0[0] + v0[1]) + (v0[2] + v0[3]) + (v1[0] + v1[1]) + (v1[2] + v1[3]);
;                         ssq += (v0[0] * v0[0] + v0[1] * v0[1]) + (v0[2] * v0[2] + v0[3] * v0[3]) + (v1[0] * v1[0] + v1[1] * v1[1]) + (v1[2] * v1[2] + v1[3] * v1[3]); }
;                     u32x4 w; w.x = pk2h(v0[0], v0[1]); w.y = pk2h(v0[2], v0[3]); w.z = pk2h(v1[0], v1[1]); w.w = pk2h(v1[2], v1[3]);
;                     if (MODE == 0 && hm) { const int cc = col0 + bj * HALF; *(u32x4*)(base + ((size_t)(row >> 11) * 16 + (cc >> 6)) * 131072 + (size_t)(row & 2047) * 64 + (cc & 63)) = w; }
;                     else *(u32x4*)(base + off + bj * HALF) = w; }
;                 if (MODE == 2) { ssum += __shfl_xor(ssum, 16); ssq += __shfl_xor(ssq, 16); ssum += __shfl_xor(ssum, 32); ssq += __shfl_xor(ssq, 32);
	v_pk_fma_f32 v[162:163], v[78:79], v[162:163], v[82:83]
	v_pk_fma_f32 v[164:165], v[80:81], v[164:165], v[84:85]
	v_pk_mul_f32 v[168:169], v[232:233], v[168:169] op_sel:[1,0]
	v_pk_mul_f32 v[166:167], v[232:233], v[166:167] op_sel:[1,0]
	v_pk_fma_f32 v[168:169], v[68:69], v[168:169], v[76:77]
	v_pk_fma_f32 v[166:167], v[66:67], v[166:167], v[74:75]
	v_pk_fma_f32 v[156:157], v[164:165], s[18:19], v[156:157] op_sel_hi:[1,0,1]
	v_pk_fma_f32 v[154:155], v[162:163], s[18:19], v[154:155] op_sel_hi:[1,0,1]
	v_pk_fma_f32 v[162:163], v[168:169], s[18:19], v[152:153] op_sel_hi:[1,0,1]
	v_pk_fma_f32 v[152:153], v[166:167], s[18:19], v[150:151] op_sel_hi:[1,0,1]
	v_pk_mov_b32 v[150:151], v[154:155], v[156:157] op_sel:[1,0]
	v_mov_b32_e32 v164, v154
	v_mov_b32_e32 v165, v157
	v_pk_add_f32 v[164:165], v[150:151], v[164:165]
	v_mul_f32_e32 v150, v154, v154
	v_pk_fma_f32 v[166:167], v[154:155], v[154:155], v[150:151] op_sel_hi:[1,1,0]
	v_mul_f32_e32 v150, v156, v156
	v_pk_fma_f32 v[168:169], v[156:157], v[156:157], v[150:151] op_sel_hi:[1,1,0]
	v_mul_f32_e32 v150, v162, v162
	v_add_f32_e32 v244, v152, v153
	v_mul_f32_e32 v239, v152, v152
	v_mul_f32_e32 v214, v153, v153
	v_pk_fma_f32 v[212:213], v[162:163], v[162:163], v[150:151] op_sel_hi:[1,1,0]
	v_cvt_pk_f16_f32 v150, v154, v155
	v_cvt_pk_f16_f32 v151, v156, v157
	v_cvt_pk_f16_f32 v152, v152, v153
	v_cvt_pk_f16_f32 v153, v162, v163
	v_mul_f32_e32 v1, v209, v209
	global_store_dwordx4 v[230:231], v[150:153], off offset:256
	v_mul_f32_e32 v245, v208, v208
	v_mov_b32_e32 v242, v162
	v_pk_add_f32 v[150:151], v[164:165], v[164:165] op_sel:[0,1] op_sel_hi:[1,0]
	v_mov_b32_e32 v240, v163
	v_mov_b32_e32 v151, v1
	v_pk_add_f32 v[154:155], v[210:211], v[210:211] op_sel:[0,1] op_sel_hi:[1,0]
	v_pk_add_f32 v[150:151], v[244:245], v[150:151]
	v_pk_add_f32 v[152:153], v[242:243], v[240:241]
	v_mov_b32_e32 v166, v208
	v_mov_b32_e32 v168, v209
	v_mov_b32_e32 v155, v214
	v_pk_add_f32 v[150:151], v[150:151], v[152:153]
	v_pk_add_f32 v[152:153], v[166:167], v[168:169]
	v_pk_add_f32 v[154:155], v[238:239], v[154:155]
	v_mov_b32_e32 v1, v213
	v_pk_add_f32 v[152:153], v[154:155], v[152:153]
	s_nop 0
	v_pk_add_f32 v[152:153], v[152:153], v[0:1]
	s_nop 0
	v_pk_add_f32 v[150:151], v[150:151], v[152:153]
	ds_bpermute_b32 v152, v228, v150
	ds_bpermute_b32 v153, v228, v151
	s_waitcnt lgkmcnt(0)
	v_pk_add_f32 v[150:151], v[150:151], v[152:153]
	ds_bpermute_b32 v152, v227, v150
	ds_bpermute_b32 v153, v227, v151
	s_and_saveexec_b64 s[22:23], s[36:37]
	s_cbranch_execz .LBB0_789
	s_waitcnt lgkmcnt(0)
	v_pk_add_f32 v[150:151], v[150:151], v[152:153]
	v_lshlrev_b64 v[152:153], 7, v[202:203]
	v_lshl_add_u64 v[152:153], s[0:1], 0, v[152:153]
	v_lshl_add_u64 v[152:153], s[16:17], 3, v[152:153]
	s_lshl_b32 s58, s72, 3
	v_lshl_add_u64 v[152:153], v[152:153], 0, s[58:59]
	global_store_dwordx2 v[152:153], v[150:151], off
.LBB0_789:
	s_or_b64 exec, exec, s[22:23]
	s_waitcnt vmcnt(6)
	s_waitcnt lgkmcnt(0)
	ds_read_b64 v[152:153], v229 offset:128
	v_cvt_f32_f16_sdwa v1, v186 dst_sel:DWORD dst_unused:UNUSED_PAD src0_sel:WORD_1
	v_cvt_f32_f16_e32 v154, v186
	v_cvt_f32_f16_sdwa v156, v187 dst_sel:DWORD dst_unused:UNUSED_PAD src0_sel:WORD_1
	v_cvt_f32_f16_e32 v162, v187
	v_cvt_f32_f16_sdwa v163, v188 dst_sel:DWORD dst_unused:UNUSED_PAD src0_sel:WORD_1
	v_cvt_f32_f16_e32 v164, v188
	v_cvt_f32_f16_sdwa v165, v189 dst_sel:DWORD dst_unused:UNUSED_PAD src0_sel:WORD_1
	v_cvt_f32_f16_e32 v166, v189
	s_waitcnt lgkmcnt(0)
	v_sub_f32_e32 v155, v1, v152
	v_sub_f32_e32 v157, v156, v152
	v_sub_f32_e32 v154, v154, v152
	v_sub_f32_e32 v156, v162, v152
	v_pk_mul_f32 v[156:157], v[152:153], v[156:157] op_sel:[1,0]
	v_pk_mul_f32 v[154:155], v[152:153], v[154:155] op_sel:[1,0]
	v_sub_f32_e32 v163, v163, v152
	v_sub_f32_e32 v165, v165, v152
	v_sub_f32_e32 v162, v164, v152
	v_sub_f32_e32 v164, v166, v152
	v_pk_fma_f32 v[154:155], v[94:95], v[154:155], v[98:99]
	v_pk_fma_f32 v[156:157], v[96:97], v[156:157], v[100:101]
	v_pk_mul_f32 v[164:165], v[152:153], v[164:165] op_sel:[1,0]
	v_pk_mul_f32 v[162:163], v[152:153], v[162:163] op_sel:[1,0]
	v_pk_fma_f32 v[164:165], v[88:89], v[164:165], v[92:93]
	v_pk_fma_f32 v[162:163], v[86:87], v[162:163], v[90:91]
	v_pk_fma_f32 v[148:149], v[156:157], s[18:19], v[148:149] op_sel_hi:[1,0,1]
	v_pk_fma_f32 v[146:147], v[154:155], s[18:19], v[146:147] op_sel_hi:[1,0,1]
	v_pk_fma_f32 v[154:155], v[164:165], s[18:19], v[144:145] op_sel_hi:[1,0,1]
	v_pk_fma_f32 v[144:145], v[162:163], s[18:19], v[142:143] op_sel_hi:[1,0,1]
	v_pk_mov_b32 v[142:143], v[146:147], v[148:149] op_sel:[1,0]
	v_mov_b32_e32 v156, v146
	v_mov_b32_e32 v157, v149
	v_pk_add_f32 v[156:157], v[142:143], v[156:157]
	v_pk_mul_f32 v[142:143], v[148:149], v[148:149]
	v_pk_mul_f32 v[164:165], v[146:147], v[146:147]
	v_lshlrev_b64 v[150:151], 10, v[220:221]
	v_pk_mov_b32 v[166:167], v[164:165], v[142:143] op_sel:[1,0]
	v_mov_b32_e32 v165, v143
	v_pk_add_f32 v[142:143], v[166:167], v[164:165]
	v_lshl_add_u64 v[150:151], v[150:151], 1, v[200:201]
	v_pk_add_f32 v[164:165], v[142:143], v[142:143] op_sel_hi:[0,1]
	v_mul_f32_e32 v142, v144, v144
	v_add_f32_e32 v162, v144, v145
	v_pk_fma_f32 v[166:167], v[144:145], v[144:145], v[142:143] op_sel_hi:[1,1,0]
	v_cvt_pk_f16_f32 v142, v146, v147
	v_cvt_pk_f16_f32 v143, v148, v149
	v_cvt_pk_f16_f32 v144, v144, v145
	v_cvt_pk_f16_f32 v145, v154, v155
	global_store_dwordx4 v[150:151], v[142:145], off
	v_cvt_f32_f16_e32 v146, v183
	v_cvt_f32_f16_sdwa v147, v184 dst_sel:DWORD dst_unused:UNUSED_PAD src0_sel:WORD_1
	v_cvt_f32_f16_sdwa v142, v182 dst_sel:DWORD dst_unused:UNUSED_PAD src0_sel:WORD_1
	v_cvt_f32_f16_e32 v144, v182
; #define PG8_LAS __attribute__((address_space(3)))
;     __device__ __forceinline__ void operator()(const f32x4 (&acc)[2][2][4][2], const Unit& u, int ui, int wr, int wc, int fr, int fq) const {
;     ...
;             for (int m = 0; m < 4; ++m) { const int row = row0 + ai * HALF + m * 16; const size_t off = (size_t)row * ldc + col0;
;                 float mu = 0.f, rs = 1.f; if (FOLD) { const f32x2_t ms = ((const PG8_LAS f32x2_t*)tb)[pslot + ai * HALF + wr * 64 + m * 16 + fr]; mu = ms.x; rs = ms.y; }
;                 float ssum = 0.f, ssq = 0.f;
; #pragma unroll
;                 for (int bj = 0; bj < 2; ++bj) { f32x4 v0 = acc[ai][bj][m][0], v1 = acc[ai][bj][m][1];
;                     if (FOLD && MODE != 2) { v0 = (v0 - mu * cv[bj][0]) * rs + bv[bj][0]; v1 = (v1 - mu * cv[bj][1]) * rs + bv[bj][1]; }
;                     if (MODE == 0) { v0 = v0 * sc; v1 = v1 * sc; }
;                     if (MODE == 1) { v0 = __builtin_elementwise_max(v0, (f32x4){0.f, 0.f, 0.f, 0.f}); v1 = __builtin_elementwise_max(v1, (f32x4){0.f, 0.f, 0.f, 0.f}); v0 = v0 * v0; v1 = v1 * v1; }
;                     if (MODE == 2) { const bf16x8 r = rr[m][bj];
;                         f32x4 h0 = (f32x4){(float)r[0], (float)r[1], (float)r[2], (float)r[3]}, h1 = (f32x4){(float)r[4], (float)r[5], (float)r[6], (float)r[7]};
;                         if (FOLD) { h0 = (h0 - mu) * rs * cv[bj][0] + bv[bj][0]; h1 = (h1 - mu) * rs * cv[bj][1] + bv[bj][1]; }
;                         v0 = v0 + alpha * h0; v1 = v1 + alpha * h1;
;                         ssum += (v0[0] + v0[1]) + (v0[2] + v0[3]) + (v1[0] + v1[1]) + (v1[2] + v1[3]);
;                         ssq += (v0[0] * v0[0] + v0[1] * v0[1]) + (v0[2] * v0[2] + v0[3] * v0[3]) + (v1[0] * v1[0] + v1[1] * v1[1]) + (v1[2] * v1[2] + v1[3] * v1[3]); }
;                     u32x4 w; w.x = pk2h(v0[0], v0[1]); w.y = pk2h(v0[2], v0[3]); w.z = pk2h(v1[0], v1[1]); w.w = pk2h(v1[2], v1[3]);
;                     if (MODE == 0 && hm) { const int cc = col0 + bj * HALF; *(u32x4*)(base + ((size_t)(row >> 11) * 16 + (cc >> 6)) * 131072 + (size_t)(row & 2047) * 64 + (cc & 63)) = w; }
;                     else *(u32x4*)(base + off + bj * HALF) = w; }
;                 if (MODE == 2) { ssum += __shfl_xor(ssum, 16); ssq += __shfl_xor(ssq, 16); ssum += __shfl_xor(ssum, 32); ssq += __shfl_xor(ssq, 32);
	v_cvt_f32_f16_sdwa v145, v183 dst_sel:DWORD dst_unused:UNUSED_PAD src0_sel:WORD_1
	v_cvt_f32_f16_e32 v148, v184
	v_cvt_f32_f16_sdwa v149, v185 dst_sel:DWORD dst_unused:UNUSED_PAD src0_sel:WORD_1
	v_cvt_f32_f16_e32 v163, v185
	v_sub_f32_e32 v143, v142, v152
	v_sub_f32_e32 v145, v145, v152
	v_sub_f32_e32 v142, v144, v152
	v_sub_f32_e32 v144, v146, v152
	v_pk_mul_f32 v[144:145], v[152:153], v[144:145] op_sel:[1,0]
	v_pk_mul_f32 v[142:143], v[152:153], v[142:143] op_sel:[1,0]
	v_sub_f32_e32 v147, v147, v152
	v_sub_f32_e32 v149, v149, v152
	v_sub_f32_e32 v146, v148, v152
	v_sub_f32_e32 v148, v163, v152
	v_pk_fma_f32 v[142:143], v[78:79], v[142:143], v[82:83]
	v_pk_fma_f32 v[144:145], v[80:81], v[144:145], v[84:85]
	v_pk_mul_f32 v[148:149], v[152:153], v[148:149] op_sel:[1,0]
	v_pk_mul_f32 v[146:147], v[152:153], v[146:147] op_sel:[1,0]
	v_pk_fma_f32 v[148:149], v[68:69], v[148:149], v[76:77]
	v_pk_fma_f32 v[146:147], v[66:67], v[146:147], v[74:75]
	v_pk_fma_f32 v[140:141], v[144:145], s[18:19], v[140:141] op_sel_hi:[1,0,1]
	v_pk_fma_f32 v[138:139], v[142:143], s[18:19], v[138:139] op_sel_hi:[1,0,1]
	v_pk_fma_f32 v[142:143], v[148:149], s[18:19], v[136:137] op_sel_hi:[1,0,1]
	v_pk_fma_f32 v[136:137], v[146:147], s[18:19], v[134:135] op_sel_hi:[1,0,1]
	v_pk_mov_b32 v[134:135], v[138:139], v[140:141] op_sel:[1,0]
	v_mov_b32_e32 v144, v138
	v_mov_b32_e32 v145, v141
	v_pk_add_f32 v[144:145], v[134:135], v[144:145]
	v_mul_f32_e32 v134, v138, v138
	v_pk_fma_f32 v[146:147], v[138:139], v[138:139], v[134:135] op_sel_hi:[1,1,0]
	v_mul_f32_e32 v134, v140, v140
	v_pk_fma_f32 v[148:149], v[140:141], v[140:141], v[134:135] op_sel_hi:[1,1,0]
	v_mul_f32_e32 v134, v142, v142
	v_add_f32_e32 v168, v136, v137
	v_mul_f32_e32 v163, v136, v136
	v_mul_f32_e32 v182, v137, v137
	v_pk_fma_f32 v[152:153], v[142:143], v[142:143], v[134:135] op_sel_hi:[1,1,0]
	v_cvt_pk_f16_f32 v134, v138, v139
	v_cvt_pk_f16_f32 v135, v140, v141
	v_cvt_pk_f16_f32 v136, v136, v137
	v_cvt_pk_f16_f32 v137, v142, v143
	v_mul_f32_e32 v1, v155, v155
	global_store_dwordx4 v[150:151], v[134:137], off offset:256
	v_mul_f32_e32 v169, v154, v154
	v_mov_b32_e32 v166, v142
	v_pk_add_f32 v[134:135], v[144:145], v[144:145] op_sel:[0,1] op_sel_hi:[1,0]
	v_mov_b32_e32 v164, v143
	v_mov_b32_e32 v135, v1
	v_pk_add_f32 v[138:139], v[156:157], v[156:157] op_sel:[0,1] op_sel_hi:[1,0]
	v_pk_add_f32 v[134:135], v[168:169], v[134:135]
	v_pk_add_f32 v[136:137], v[166:167], v[164:165]
	v_mov_b32_e32 v146, v154
	v_mov_b32_e32 v148, v155
	v_mov_b32_e32 v139, v182
	v_pk_add_f32 v[134:135], v[134:135], v[136:137]
	v_pk_add_f32 v[136:137], v[146:147], v[148:149]
	v_pk_add_f32 v[138:139], v[162:163], v[138:139]
	v_mov_b32_e32 v1, v153
	v_pk_add_f32 v[136:137], v[138:139], v[136:137]
	s_nop 0
	v_pk_add_f32 v[136:137], v[136:137], v[0:1]
	s_nop 0
	v_pk_add_f32 v[134:135], v[134:135], v[136:137]
	ds_bpermute_b32 v136, v228, v134
	ds_bpermute_b32 v137, v228, v135
	s_waitcnt lgkmcnt(0)
	v_pk_add_f32 v[134:135], v[134:135], v[136:137]
	ds_bpermute_b32 v136, v227, v134
	ds_bpermute_b32 v137, v227, v135
	s_and_saveexec_b64 s[22:23], s[36:37]
	s_cbranch_execz .LBB0_791
	s_waitcnt lgkmcnt(0)
	v_pk_add_f32 v[134:135], v[134:135], v[136:137]
	v_lshlrev_b64 v[136:137], 7, v[220:221]
	v_lshl_add_u64 v[136:137], s[0:1], 0, v[136:137]
	v_lshl_add_u64 v[136:137], s[16:17], 3, v[136:137]
	s_lshl_b32 s58, s72, 3
	v_lshl_add_u64 v[136:137], v[136:137], 0, s[58:59]
	global_store_dwordx2 v[136:137], v[134:135], off
.LBB0_791:
	s_or_b64 exec, exec, s[22:23]
	s_waitcnt vmcnt(6)
	s_waitcnt lgkmcnt(0)
	ds_read_b64 v[136:137], v229 offset:256
	v_cvt_f32_f16_sdwa v1, v178 dst_sel:DWORD dst_unused:UNUSED_PAD src0_sel:WORD_1
	v_cvt_f32_f16_e32 v138, v178
	v_cvt_f32_f16_sdwa v140, v179 dst_sel:DWORD dst_unused:UNUSED_PAD src0_sel:WORD_1
	v_cvt_f32_f16_e32 v142, v179
	v_cvt_f32_f16_sdwa v143, v180 dst_sel:DWORD dst_unused:UNUSED_PAD src0_sel:WORD_1
	v_cvt_f32_f16_e32 v144, v180
	v_cvt_f32_f16_sdwa v145, v181 dst_sel:DWORD dst_unused:UNUSED_PAD src0_sel:WORD_1
	v_cvt_f32_f16_e32 v146, v181
	s_waitcnt lgkmcnt(0)
	v_sub_f32_e32 v139, v1, v136
	v_sub_f32_e32 v141, v140, v136
	v_sub_f32_e32 v138, v138, v136
	v_sub_f32_e32 v140, v142, v136
	v_pk_mul_f32 v[140:141], v[136:137], v[140:141] op_sel:[1,0]
	v_pk_mul_f32 v[138:139], v[136:137], v[138:139] op_sel:[1,0]
	v_sub_f32_e32 v143, v143, v136
	v_sub_f32_e32 v145, v145, v136
	v_sub_f32_e32 v142, v144, v136
	v_sub_f32_e32 v144, v146, v136
	v_pk_fma_f32 v[138:139], v[94:95], v[138:139], v[98:99]
	v_pk_fma_f32 v[140:141], v[96:97], v[140:141], v[100:101]
	v_pk_mul_f32 v[144:145], v[136:137], v[144:145] op_sel:[1,0]
	v_pk_mul_f32 v[142:143], v[136:137], v[142:143] op_sel:[1,0]
	v_pk_fma_f32 v[144:145], v[88:89], v[144:145], v[92:93]
	v_pk_fma_f32 v[142:143], v[86:87], v[142:143], v[90:91]
	v_pk_fma_f32 v[132:133], v[140:141], s[18:19], v[132:133] op_sel_hi:[1,0,1]
	v_pk_fma_f32 v[130:131], v[138:139], s[18:19], v[130:131] op_sel_hi:[1,0,1]
	v_pk_fma_f32 v[138:139], v[144:145], s[18:19], v[128:129] op_sel_hi:[1,0,1]
	v_pk_fma_f32 v[128:129], v[142:143], s[18:19], v[126:127] op_sel_hi:[1,0,1]
	v_pk_mov_b32 v[126:127], v[130:131], v[132:133] op_sel:[1,0]
	v_mov_b32_e32 v140, v130
	v_mov_b32_e32 v141, v133
	v_pk_add_f32 v[140:141], v[126:127], v[140:141]
	v_pk_mul_f32 v[126:127], v[132:133], v[132:133]
	v_pk_mul_f32 v[144:145], v[130:131], v[130:131]
	v_lshlrev_b64 v[134:135], 10, v[218:219]
	v_pk_mov_b32 v[146:147], v[144:145], v[126:127] op_sel:[1,0]
	v_mov_b32_e32 v145, v127
	v_pk_add_f32 v[126:127], v[146:147], v[144:145]
	v_lshl_add_u64 v[134:135], v[134:135], 1, v[200:201]
	v_pk_add_f32 v[144:145], v[126:127], v[126:127] op_sel_hi:[0,1]
; #define PG8_LAS __attribute__((address_space(3)))
;     __device__ __forceinline__ void operator()(const f32x4 (&acc)[2][2][4][2], const Unit& u, int ui, int wr, int wc, int fr, int fq) const {
;     ...
;             for (int m = 0; m < 4; ++m) { const int row = row0 + ai * HALF + m * 16; const size_t off = (size_t)row * ldc + col0;
;                 float mu = 0.f, rs = 1.f; if (FOLD) { const f32x2_t ms = ((const PG8_LAS f32x2_t*)tb)[pslot + ai * HALF + wr * 64 + m * 16 + fr]; mu = ms.x; rs = ms.y; }
;                 float ssum = 0.f, ssq = 0.f;
; #pragma unroll
;                 for (int bj = 0; bj < 2; ++bj) { f32x4 v0 = acc[ai][bj][m][0], v1 = acc[ai][bj][m][1];
;                     if (FOLD && MODE != 2) { v0 = (v0 - mu * cv[bj][0]) * rs + bv[bj][0]; v1 = (v1 - mu * cv[bj][1]) * rs + bv[bj][1]; }
;                     if (MODE == 0) { v0 = v0 * sc; v1 = v1 * sc; }
;                     if (MODE == 1) { v0 = __builtin_elementwise_max(v0, (f32x4){0.f, 0.f, 0.f, 0.f}); v1 = __builtin_elementwise_max(v1, (f32x4){0.f, 0.f, 0.f, 0.f}); v0 = v0 * v0; v1 = v1 * v1; }
;                     if (MODE == 2) { const bf16x8 r = rr[m][bj];
;                         f32x4 h0 = (f32x4){(float)r[0], (float)r[1], (float)r[2], (float)r[3]}, h1 = (f32x4){(float)r[4], (float)r[5], (float)r[6], (float)r[7]};
;                         if (FOLD) { h0 = (h0 - mu) * rs * cv[bj][0] + bv[bj][0]; h1 = (h1 - mu) * rs * cv[bj][1] + bv[bj][1]; }
;                         v0 = v0 + alpha * h0; v1 = v1 + alpha * h1;
;                         ssum += (v0[0] + v0[1]) + (v0[2] + v0[3]) + (v1[0] + v1[1]) + (v1[2] + v1[3]);
;                         ssq += (v0[0] * v0[0] + v0[1] * v0[1]) + (v0[2] * v0[2] + v0[3] * v0[3]) + (v1[0] * v1[0] + v1[1] * v1[1]) + (v1[2] * v1[2] + v1[3] * v1[3]); }
;                     u32x4 w; w.x = pk2h(v0[0], v0[1]); w.y = pk2h(v0[2], v0[3]); w.z = pk2h(v1[0], v1[1]); w.w = pk2h(v1[2], v1[3]);
;                     if (MODE == 0 && hm) { const int cc = col0 + bj * HALF; *(u32x4*)(base + ((size_t)(row >> 11) * 16 + (cc >> 6)) * 131072 + (size_t)(row & 2047) * 64 + (cc & 63)) = w; }
;                     else *(u32x4*)(base + off + bj * HALF) = w; }
;                 if (MODE == 2) { ssum += __shfl_xor(ssum, 16); ssq += __shfl_xor(ssq, 16); ssum += __shfl_xor(ssum, 32); ssq += __shfl_xor(ssq, 32);
	v_mul_f32_e32 v126, v128, v128
	v_add_f32_e32 v142, v128, v129
	v_pk_fma_f32 v[146:147], v[128:129], v[128:129], v[126:127] op_sel_hi:[1,1,0]
	v_cvt_pk_f16_f32 v126, v130, v131
	v_cvt_pk_f16_f32 v127, v132, v133
	v_cvt_pk_f16_f32 v128, v128, v129
	v_cvt_pk_f16_f32 v129, v138, v139
	global_store_dwordx4 v[134:135], v[126:129], off
	v_cvt_f32_f16_e32 v130, v175
	v_cvt_f32_f16_sdwa v131, v176 dst_sel:DWORD dst_unused:UNUSED_PAD src0_sel:WORD_1
	v_cvt_f32_f16_sdwa v126, v174 dst_sel:DWORD dst_unused:UNUSED_PAD src0_sel:WORD_1
	v_cvt_f32_f16_e32 v128, v174
	v_cvt_f32_f16_sdwa v129, v175 dst_sel:DWORD dst_unused:UNUSED_PAD src0_sel:WORD_1
	v_cvt_f32_f16_e32 v132, v176
	v_cvt_f32_f16_sdwa v133, v177 dst_sel:DWORD dst_unused:UNUSED_PAD src0_sel:WORD_1
	v_cvt_f32_f16_e32 v143, v177
	v_sub_f32_e32 v127, v126, v136
	v_sub_f32_e32 v129, v129, v136
	v_sub_f32_e32 v126, v128, v136
	v_sub_f32_e32 v128, v130, v136
	v_pk_mul_f32 v[128:129], v[136:137], v[128:129] op_sel:[1,0]
	v_pk_mul_f32 v[126:127], v[136:137], v[126:127] op_sel:[1,0]
	v_sub_f32_e32 v131, v131, v136
	v_sub_f32_e32 v133, v133, v136
	v_sub_f32_e32 v130, v132, v136
	v_sub_f32_e32 v132, v143, v136
	v_pk_fma_f32 v[126:127], v[78:79], v[126:127], v[82:83]
	v_pk_fma_f32 v[128:129], v[80:81], v[128:129], v[84:85]
	v_pk_mul_f32 v[132:133], v[136:137], v[132:133] op_sel:[1,0]
	v_pk_mul_f32 v[130:131], v[136:137], v[130:131] op_sel:[1,0]
	v_pk_fma_f32 v[132:133], v[68:69], v[132:133], v[76:77]
	v_pk_fma_f32 v[130:131], v[66:67], v[130:131], v[74:75]
	v_pk_fma_f32 v[124:125], v[128:129], s[18:19], v[124:125] op_sel_hi:[1,0,1]
	v_pk_fma_f32 v[122:123], v[126:127], s[18:19], v[122:123] op_sel_hi:[1,0,1]
	v_pk_fma_f32 v[126:127], v[132:133], s[18:19], v[120:121] op_sel_hi:[1,0,1]
	v_pk_fma_f32 v[120:121], v[130:131], s[18:19], v[118:119] op_sel_hi:[1,0,1]
	v_pk_mov_b32 v[118:119], v[122:123], v[124:125] op_sel:[1,0]
	v_mov_b32_e32 v128, v122
	v_mov_b32_e32 v129, v125
	v_pk_add_f32 v[128:129], v[118:119], v[128:129]
	v_mul_f32_e32 v118, v122, v122
	v_pk_fma_f32 v[130:131], v[122:123], v[122:123], v[118:119] op_sel_hi:[1,1,0]
	v_mul_f32_e32 v118, v124, v124
	v_pk_fma_f32 v[132:133], v[124:125], v[124:125], v[118:119] op_sel_hi:[1,1,0]
	v_mul_f32_e32 v118, v126, v126
	v_add_f32_e32 v148, v120, v121
	v_mul_f32_e32 v143, v120, v120
	v_mul_f32_e32 v150, v121, v121
	v_pk_fma_f32 v[136:137], v[126:127], v[126:127], v[118:119] op_sel_hi:[1,1,0]
	v_cvt_pk_f16_f32 v118, v122, v123
	v_cvt_pk_f16_f32 v119, v124, v125
	v_cvt_pk_f16_f32 v120, v120, v121
	v_cvt_pk_f16_f32 v121, v126, v127
	v_mul_f32_e32 v1, v139, v139
	global_store_dwordx4 v[134:135], v[118:121], off offset:256
	v_mul_f32_e32 v149, v138, v138
	v_mov_b32_e32 v146, v126
	v_pk_add_f32 v[118:119], v[128:129], v[128:129] op_sel:[0,1] op_sel_hi:[1,0]
	v_mov_b32_e32 v144, v127
	v_mov_b32_e32 v119, v1
	v_pk_add_f32 v[122:123], v[140:141], v[140:141] op_sel:[0,1] op_sel_hi:[1,0]
	v_pk_add_f32 v[118:119], v[148:149], v[118:119]
	v_pk_add_f32 v[120:121], v[146:147], v[144:145]
	v_mov_b32_e32 v130, v138
	v_mov_b32_e32 v132, v139
	v_mov_b32_e32 v123, v150
	v_pk_add_f32 v[118:119], v[118:119], v[120:121]
	v_pk_add_f32 v[120:121], v[130:131], v[132:133]
	v_pk_add_f32 v[122:123], v[142:143], v[122:123]
	v_mov_b32_e32 v1, v137
	v_pk_add_f32 v[120:121], v[122:123], v[120:121]
	s_nop 0
	v_pk_add_f32 v[120:121], v[120:121], v[0:1]
	s_nop 0
	v_pk_add_f32 v[118:119], v[118:119], v[120:121]
	ds_bpermute_b32 v120, v228, v118
	ds_bpermute_b32 v121, v228, v119
	s_waitcnt lgkmcnt(0)
	v_pk_add_f32 v[118:119], v[118:119], v[120:121]
	ds_bpermute_b32 v120, v227, v118
	ds_bpermute_b32 v121, v227, v119
	s_and_saveexec_b64 s[22:23], s[36:37]
	v_readlane_b32 s54, v255, 25
	v_readlane_b32 s55, v255, 26
	s_cbranch_execz .LBB0_793
	s_waitcnt lgkmcnt(0)
	v_pk_add_f32 v[118:119], v[118:119], v[120:121]
	v_lshlrev_b64 v[120:121], 7, v[218:219]
	v_lshl_add_u64 v[120:121], s[0:1], 0, v[120:121]
	v_lshl_add_u64 v[120:121], s[16:17], 3, v[120:121]
	s_lshl_b32 s58, s72, 3
	v_lshl_add_u64 v[120:121], v[120:121], 0, s[58:59]
	global_store_dwordx2 v[120:121], v[118:119], off
; #define PG8_LAS __attribute__((address_space(3)))
;     __device__ __forceinline__ void operator()(const f32x4 (&acc)[2][2][4][2], const Unit& u, int ui, int wr, int wc, int fr, int fq) const {
;     ...
;             for (int m = 0; m < 4; ++m) { const int row = row0 + ai * HALF + m * 16; const size_t off = (size_t)row * ldc + col0;
;                 float mu = 0.f, rs = 1.f; if (FOLD) { const f32x2_t ms = ((const PG8_LAS f32x2_t*)tb)[pslot + ai * HALF + wr * 64 + m * 16 + fr]; mu = ms.x; rs = ms.y; }
;                 float ssum = 0.f, ssq = 0.f;
; #pragma unroll
;                 for (int bj = 0; bj < 2; ++bj) { f32x4 v0 = acc[ai][bj][m][0], v1 = acc[ai][bj][m][1];
;                     if (FOLD && MODE != 2) { v0 = (v0 - mu * cv[bj][0]) * rs + bv[bj][0]; v1 = (v1 - mu * cv[bj][1]) * rs + bv[bj][1]; }
;                     if (MODE == 0) { v0 = v0 * sc; v1 = v1 * sc; }
;                     if (MODE == 1) { v0 = __builtin_elementwise_max(v0, (f32x4){0.f, 0.f, 0.f, 0.f}); v1 = __builtin_elementwise_max(v1, (f32x4){0.f, 0.f, 0.f, 0.f}); v0 = v0 * v0; v1 = v1 * v1; }
;                     if (MODE == 2) { const bf16x8 r = rr[m][bj];
;                         f32x4 h0 = (f32x4){(float)r[0], (float)r[1], (float)r[2], (float)r[3]}, h1 = (f32x4){(float)r[4], (float)r[5], (float)r[6], (float)r[7]};
;                         if (FOLD) { h0 = (h0 - mu) * rs * cv[bj][0] + bv[bj][0]; h1 = (h1 - mu) * rs * cv[bj][1] + bv[bj][1]; }
;                         v0 = v0 + alpha * h0; v1 = v1 + alpha * h1;
;                         ssum += (v0[0] + v0[1]) + (v0[2] + v0[3]) + (v1[0] + v1[1]) + (v1[2] + v1[3]);
;                         ssq += (v0[0] * v0[0] + v0[1] * v0[1]) + (v0[2] * v0[2] + v0[3] * v0[3]) + (v1[0] * v1[0] + v1[1] * v1[1]) + (v1[2] * v1[2] + v1[3] * v1[3]); }
;                     u32x4 w; w.x = pk2h(v0[0], v0[1]); w.y = pk2h(v0[2], v0[3]); w.z = pk2h(v1[0], v1[1]); w.w = pk2h(v1[2], v1[3]);
;                     if (MODE == 0 && hm) { const int cc = col0 + bj * HALF; *(u32x4*)(base + ((size_t)(row >> 11) * 16 + (cc >> 6)) * 131072 + (size_t)(row & 2047) * 64 + (cc & 63)) = w; }
;                     else *(u32x4*)(base + off + bj * HALF) = w; }
;                 if (MODE == 2) { ssum += __shfl_xor(ssum, 16); ssq += __shfl_xor(ssq, 16); ssum += __shfl_xor(ssum, 32); ssq += __shfl_xor(ssq, 32);
.LBB0_793:
	s_or_b64 exec, exec, s[22:23]
	s_waitcnt vmcnt(6)
	s_waitcnt lgkmcnt(0)
	ds_read_b64 v[120:121], v229 offset:384
	v_cvt_f32_f16_sdwa v1, v170 dst_sel:DWORD dst_unused:UNUSED_PAD src0_sel:WORD_1
	v_cvt_f32_f16_e32 v122, v170
	v_cvt_f32_f16_sdwa v124, v171 dst_sel:DWORD dst_unused:UNUSED_PAD src0_sel:WORD_1
	v_cvt_f32_f16_e32 v126, v171
	v_cvt_f32_f16_sdwa v127, v172 dst_sel:DWORD dst_unused:UNUSED_PAD src0_sel:WORD_1
	v_cvt_f32_f16_e32 v128, v172
	v_cvt_f32_f16_sdwa v129, v173 dst_sel:DWORD dst_unused:UNUSED_PAD src0_sel:WORD_1
	v_cvt_f32_f16_e32 v130, v173
	s_waitcnt lgkmcnt(0)
	v_sub_f32_e32 v123, v1, v120
	v_sub_f32_e32 v125, v124, v120
	v_sub_f32_e32 v122, v122, v120
	v_sub_f32_e32 v124, v126, v120
	v_pk_mul_f32 v[124:125], v[120:121], v[124:125] op_sel:[1,0]
	v_pk_mul_f32 v[122:123], v[120:121], v[122:123] op_sel:[1,0]
	v_sub_f32_e32 v127, v127, v120
	v_sub_f32_e32 v129, v129, v120
	v_sub_f32_e32 v126, v128, v120
	v_sub_f32_e32 v128, v130, v120
	v_pk_fma_f32 v[122:123], v[94:95], v[122:123], v[98:99]
	v_pk_fma_f32 v[124:125], v[96:97], v[124:125], v[100:101]
	v_pk_mul_f32 v[128:129], v[120:121], v[128:129] op_sel:[1,0]
	v_pk_mul_f32 v[126:127], v[120:121], v[126:127] op_sel:[1,0]
	v_pk_fma_f32 v[128:129], v[88:89], v[128:129], v[92:93]
	v_pk_fma_f32 v[126:127], v[86:87], v[126:127], v[90:91]
	v_pk_fma_f32 v[116:117], v[124:125], s[18:19], v[116:117] op_sel_hi:[1,0,1]
	v_pk_fma_f32 v[114:115], v[122:123], s[18:19], v[114:115] op_sel_hi:[1,0,1]
	v_pk_fma_f32 v[122:123], v[128:129], s[18:19], v[112:113] op_sel_hi:[1,0,1]
	v_pk_fma_f32 v[112:113], v[126:127], s[18:19], v[110:111] op_sel_hi:[1,0,1]
	v_pk_mov_b32 v[110:111], v[114:115], v[116:117] op_sel:[1,0]
	v_mov_b32_e32 v124, v114
	v_mov_b32_e32 v125, v117
	v_pk_add_f32 v[124:125], v[110:111], v[124:125]
	v_pk_mul_f32 v[110:111], v[116:117], v[116:117]
	v_pk_mul_f32 v[128:129], v[114:115], v[114:115]
	v_lshlrev_b64 v[118:119], 10, v[206:207]
	v_pk_mov_b32 v[130:131], v[128:129], v[110:111] op_sel:[1,0]
	v_mov_b32_e32 v129, v111
	v_pk_add_f32 v[110:111], v[130:131], v[128:129]
	v_lshl_add_u64 v[118:119], v[118:119], 1, v[200:201]
	v_pk_add_f32 v[128:129], v[110:111], v[110:111] op_sel_hi:[0,1]
	v_mul_f32_e32 v110, v112, v112
	v_add_f32_e32 v126, v112, v113
	v_pk_fma_f32 v[130:131], v[112:113], v[112:113], v[110:111] op_sel_hi:[1,1,0]
	v_cvt_pk_f16_f32 v110, v114, v115
	v_cvt_pk_f16_f32 v111, v116, v117
	v_cvt_pk_f16_f32 v112, v112, v113
	v_cvt_pk_f16_f32 v113, v122, v123
	global_store_dwordx4 v[118:119], v[110:113], off
	v_cvt_f32_f16_e32 v114, v159
	v_cvt_f32_f16_sdwa v115, v160 dst_sel:DWORD dst_unused:UNUSED_PAD src0_sel:WORD_1
	v_cvt_f32_f16_sdwa v110, v158 dst_sel:DWORD dst_unused:UNUSED_PAD src0_sel:WORD_1
	v_cvt_f32_f16_e32 v112, v158
	v_cvt_f32_f16_sdwa v113, v159 dst_sel:DWORD dst_unused:UNUSED_PAD src0_sel:WORD_1
	v_cvt_f32_f16_e32 v116, v160
	v_cvt_f32_f16_sdwa v117, v161 dst_sel:DWORD dst_unused:UNUSED_PAD src0_sel:WORD_1
	v_cvt_f32_f16_e32 v127, v161
	v_sub_f32_e32 v111, v110, v120
	v_sub_f32_e32 v113, v113, v120
	v_sub_f32_e32 v110, v112, v120
	v_sub_f32_e32 v112, v114, v120
	v_pk_mul_f32 v[112:113], v[120:121], v[112:113] op_sel:[1,0]
	v_pk_mul_f32 v[110:111], v[120:121], v[110:111] op_sel:[1,0]
	v_sub_f32_e32 v115, v115, v120
	v_sub_f32_e32 v117, v117, v120
	v_sub_f32_e32 v114, v116, v120
	v_sub_f32_e32 v116, v127, v120
	v_pk_fma_f32 v[110:111], v[78:79], v[110:111], v[82:83]
	v_pk_fma_f32 v[112:113], v[80:81], v[112:113], v[84:85]
	v_pk_mul_f32 v[116:117], v[120:121], v[116:117] op_sel:[1,0]
	v_pk_mul_f32 v[114:115], v[120:121], v[114:115] op_sel:[1,0]
	v_pk_fma_f32 v[116:117], v[68:69], v[116:117], v[76:77]
	v_pk_fma_f32 v[114:115], v[66:67], v[114:115], v[74:75]
	v_pk_fma_f32 v[108:109], v[112:113], s[18:19], v[108:109] op_sel_hi:[1,0,1]
	v_pk_fma_f32 v[106:107], v[110:111], s[18:19], v[106:107] op_sel_hi:[1,0,1]
	v_pk_fma_f32 v[110:111], v[116:117], s[18:19], v[104:105] op_sel_hi:[1,0,1]
	v_pk_fma_f32 v[104:105], v[114:115], s[18:19], v[102:103] op_sel_hi:[1,0,1]
	v_pk_mov_b32 v[102:103], v[106:107], v[108:109] op_sel:[1,0]
	v_mov_b32_e32 v112, v106
	v_mov_b32_e32 v113, v109
	v_pk_add_f32 v[112:113], v[102:103], v[112:113]
	v_mul_f32_e32 v102, v106, v106
	v_pk_fma_f32 v[114:115], v[106:107], v[106:107], v[102:103] op_sel_hi:[1,1,0]
	v_mul_f32_e32 v102, v108, v108
	v_pk_fma_f32 v[116:117], v[108:109], v[108:109], v[102:103] op_sel_hi:[1,1,0]
	v_mul_f32_e32 v102, v110, v110
	v_add_f32_e32 v132, v104, v105
	v_mul_f32_e32 v127, v104, v104
	v_mul_f32_e32 v134, v105, v105
	v_pk_fma_f32 v[120:121], v[110:111], v[110:111], v[102:103] op_sel_hi:[1,1,0]
	v_cvt_pk_f16_f32 v102, v106, v107
	v_cvt_pk_f16_f32 v103, v108, v109
	v_cvt_pk_f16_f32 v104, v104, v105
	v_cvt_pk_f16_f32 v105, v110, v111
	v_mul_f32_e32 v1, v123, v123
	global_store_dwordx4 v[118:119], v[102:105], off offset:256
	v_mul_f32_e32 v133, v122, v122
	v_mov_b32_e32 v130, v110
	v_pk_add_f32 v[102:103], v[112:113], v[112:113] op_sel:[0,1] op_sel_hi:[1,0]
	v_mov_b32_e32 v128, v111
	v_mov_b32_e32 v103, v1
	v_pk_add_f32 v[106:107], v[124:125], v[124:125] op_sel:[0,1] op_sel_hi:[1,0]
	v_pk_add_f32 v[102:103], v[132:133], v[102:103]
	v_pk_add_f32 v[104:105], v[130:131], v[128:129]
	v_mov_b32_e32 v114, v122
	v_mov_b32_e32 v116, v123
	v_mov_b32_e32 v107, v134
	v_pk_add_f32 v[102:103], v[102:103], v[104:105]
	v_pk_add_f32 v[104:105], v[114:115], v[116:117]
	v_pk_add_f32 v[106:107], v[126:127], v[106:107]
	v_mov_b32_e32 v1, v121
	v_pk_add_f32 v[104:105], v[106:107], v[104:105]
	s_nop 0
	v_pk_add_f32 v[104:105], v[104:105], v[0:1]
	s_nop 0
	v_pk_add_f32 v[102:103], v[102:103], v[104:105]
	ds_bpermute_b32 v104, v228, v102
	ds_bpermute_b32 v105, v228, v103
	s_waitcnt lgkmcnt(0)
	v_pk_add_f32 v[102:103], v[102:103], v[104:105]
	ds_bpermute_b32 v104, v227, v102
	ds_bpermute_b32 v105, v227, v103
	s_and_saveexec_b64 s[22:23], s[36:37]
	s_cbranch_execz .LBB0_795
	s_waitcnt lgkmcnt(0)
	v_pk_add_f32 v[102:103], v[102:103], v[104:105]
	v_lshlrev_b64 v[104:105], 7, v[206:207]
	v_lshl_add_u64 v[104:105], s[0:1], 0, v[104:105]
	v_lshl_add_u64 v[104:105], s[16:17], 3, v[104:105]
	s_lshl_b32 s58, s72, 3
	v_lshl_add_u64 v[104:105], v[104:105], 0, s[58:59]
	global_store_dwordx2 v[104:105], v[102:103], off

; #define PG8_LAS __attribute__((address_space(3)))
;     __device__ __forceinline__ void operator()(const f32x4 (&acc)[2][2][4][2], const Unit& u, int ui, int wr, int wc, int fr, int fq) const {
;     ...
;         for (int ai = 0; ai < 2; ++ai) {
;         bf16x8 rr[4][2];
;         if (MODE == 2) {
; #pragma unroll
;             for (int m = 0; m < 4; ++m)
; #pragma unroll
;                 for (int bj = 0; bj < 2; ++bj) rr[m][bj] = *(const bf16x8*)(R + (size_t)(row0 + ai * HALF + m * 16) * ldc + col0 + bj * HALF);
;             __builtin_amdgcn_sched_barrier(0); }
; #pragma unroll
;             for (int m = 0; m < 4; ++m) { const int row = row0 + ai * HALF + m * 16; const size_t off = (size_t)row * ldc + col0;
;                 float mu = 0.f, rs = 1.f; if (FOLD) { const f32x2_t ms = ((const PG8_LAS f32x2_t*)tb)[pslot + ai * HALF + wr * 64 + m * 16 + fr]; mu = ms.x; rs = ms.y; }
;                 float ssum = 0.f, ssq = 0.f;
; #pragma unroll
;                 for (int bj = 0; bj < 2; ++bj) { f32x4 v0 = acc[ai][bj][m][0], v1 = acc[ai][bj][m][1];
;                     if (FOLD && MODE != 2) { v0 = (v0 - mu * cv[bj][0]) * rs + bv[bj][0]; v1 = (v1 - mu * cv[bj][1]) * rs + bv[bj][1]; }
;                     if (MODE == 0) { v0 = v0 * sc; v1 = v1 * sc; }
;                     if (MODE == 1) { v0 = __builtin_elementwise_max(v0, (f32x4){0.f, 0.f, 0.f, 0.f}); v1 = __builtin_elementwise_max(v1, (f32x4){0.f, 0.f, 0.f, 0.f}); v0 = v0 * v0; v1 = v1 * v1; }
;                     if (MODE == 2) { const bf16x8 r = rr[m][bj];
;                         f32x4 h0 = (f32x4){(float)r[0], (float)r[1], (float)r[2], (float)r[3]}, h1 = (f32x4){(float)r[4], (float)r[5], (float)r[6], (float)r[7]};
;                         if (FOLD) { h0 = (h0 - mu) * rs * cv[bj][0] + bv[bj][0]; h1 = (h1 - mu) * rs * cv[bj][1] + bv[bj][1]; }
;                         v0 = v0 + alpha * h0; v1 = v1 + alpha * h1;
;                         ssum += (v0[0] + v0[1]) + (v0[2] + v0[3]) + (v1[0] + v1[1]) + (v1[2] + v1[3]);
;                         ssq += (v0[0] * v0[0] + v0[1] * v0[1]) + (v0[2] * v0[2] + v0[3] * v0[3]) + (v1[0] * v1[0] + v1[1] * v1[1]) + (v1[2] * v1[2] + v1[3] * v1[3]); }
;                     u32x4 w; w.x = pk2h(v0[0], v0[1]); w.y = pk2h(v0[2], v0[3]); w.z = pk2h(v1[0], v1[1]); w.w = pk2h(v1[2], v1[3]);
.LBB0_827:
	v_lshl_or_b32 v126, s20, 8, v181
	v_lshl_add_u32 v170, s26, 8, v17
	v_ashrrev_i32_e32 v127, 31, v126
	v_readlane_b32 s12, v254, 47
	v_lshlrev_b64 v[168:169], 1, v[126:127]
	v_readlane_b32 s13, v254, 48
	v_ashrrev_i32_e32 v171, 31, v170
	v_lshlrev_b64 v[194:195], 11, v[170:171]
	v_lshl_add_u64 v[172:173], s[12:13], 0, v[168:169]
	v_or_b32_e32 v178, 16, v170
	v_lshl_add_u64 v[126:127], v[172:173], 0, v[194:195]
	v_ashrrev_i32_e32 v179, 31, v178
	global_load_dwordx4 v[186:189], v[126:127], off
	global_load_dwordx4 v[190:193], v[126:127], off offset:256
	v_lshlrev_b64 v[126:127], 11, v[178:179]
	v_or_b32_e32 v176, 32, v170
	v_lshl_add_u64 v[126:127], v[172:173], 0, v[126:127]
	v_ashrrev_i32_e32 v177, 31, v176
	global_load_dwordx4 v[154:157], v[126:127], off
	global_load_dwordx4 v[150:153], v[126:127], off offset:256
	v_lshlrev_b64 v[126:127], 11, v[176:177]
	v_or_b32_e32 v174, 48, v170
	v_lshl_add_u64 v[126:127], v[172:173], 0, v[126:127]
	v_ashrrev_i32_e32 v175, 31, v174
	global_load_dwordx4 v[146:149], v[126:127], off
	global_load_dwordx4 v[142:145], v[126:127], off offset:256
	v_lshlrev_b64 v[126:127], 11, v[174:175]
	v_lshl_add_u64 v[126:127], v[172:173], 0, v[126:127]
	global_load_dwordx4 v[138:141], v[126:127], off
	s_nop 0
	global_load_dwordx4 v[126:129], v[126:127], off offset:256
	v_and_b32_e32 v183, 64, v237
	v_xor_b32_e32 v1, 16, v237
	v_add_u32_e32 v183, 64, v183
	v_cmp_lt_i32_e32 vcc, v1, v183
	s_lshl_b32 s82, s20, 2
	v_lshl_add_u64 v[168:169], s[56:57], 0, v[168:169]
	v_cndmask_b32_e32 v1, v237, v1, vcc
	v_lshlrev_b32_e32 v184, 2, v1
	v_xor_b32_e32 v1, 32, v237
	v_cmp_lt_i32_e32 vcc, v1, v183
	s_ashr_i32 s83, s82, 31
	s_nop 0
	v_cndmask_b32_e32 v1, v237, v1, vcc
	v_lshlrev_b32_e32 v183, 2, v1
	s_waitcnt vmcnt(6)
	v_cvt_f32_f16_e32 v196, v186
	v_cvt_f32_f16_sdwa v197, v186 dst_sel:DWORD dst_unused:UNUSED_PAD src0_sel:WORD_1
	v_cvt_f32_f16_e32 v186, v187
	v_cvt_f32_f16_sdwa v187, v187 dst_sel:DWORD dst_unused:UNUSED_PAD src0_sel:WORD_1
	v_cvt_f32_f16_e32 v198, v188
	v_cvt_f32_f16_sdwa v199, v188 dst_sel:DWORD dst_unused:UNUSED_PAD src0_sel:WORD_1
	v_cvt_f32_f16_e32 v188, v189
	v_cvt_f32_f16_sdwa v189, v189 dst_sel:DWORD dst_unused:UNUSED_PAD src0_sel:WORD_1
	v_pk_fma_f32 v[136:137], v[186:187], s[18:19], v[136:137] op_sel_hi:[1,0,1]
	v_pk_fma_f32 v[134:135], v[196:197], s[18:19], v[134:135] op_sel_hi:[1,0,1]
	v_lshl_add_u64 v[194:195], v[168:169], 0, v[194:195]
	v_pk_fma_f32 v[186:187], v[188:189], s[18:19], v[132:133] op_sel_hi:[1,0,1]
	v_pk_fma_f32 v[132:133], v[198:199], s[18:19], v[130:131] op_sel_hi:[1,0,1]
	v_pk_mov_b32 v[130:131], v[134:135], v[136:137] op_sel:[1,0]
	v_mov_b32_e32 v188, v134
	v_mov_b32_e32 v189, v137
	v_pk_add_f32 v[188:189], v[130:131], v[188:189]
	v_pk_mul_f32 v[130:131], v[136:137], v[136:137]
	v_pk_mul_f32 v[198:199], v[134:135], v[134:135]
	v_add_f32_e32 v196, v132, v133
	v_pk_mov_b32 v[200:201], v[198:199], v[130:131] op_sel:[1,0]
	v_mov_b32_e32 v199, v131
	v_pk_add_f32 v[130:131], v[200:201], v[198:199]
	v_mul_f32_e32 v1, v187, v187
	v_pk_add_f32 v[198:199], v[130:131], v[130:131] op_sel_hi:[0,1]
	v_mul_f32_e32 v130, v132, v132
	v_pk_fma_f32 v[200:201], v[132:133], v[132:133], v[130:131] op_sel_hi:[1,1,0]
	v_cvt_pk_f16_f32 v130, v134, v135
	v_cvt_pk_f16_f32 v131, v136, v137
	v_cvt_pk_f16_f32 v132, v132, v133
	v_cvt_pk_f16_f32 v133, v186, v187
	global_store_dwordx4 v[194:195], v[130:133], off
	v_cvt_f32_f16_e32 v134, v192
	v_cvt_f32_f16_sdwa v135, v192 dst_sel:DWORD dst_unused:UNUSED_PAD src0_sel:WORD_1
	v_cvt_f32_f16_e32 v130, v190
	v_cvt_f32_f16_sdwa v131, v190 dst_sel:DWORD dst_unused:UNUSED_PAD src0_sel:WORD_1
	v_cvt_f32_f16_e32 v132, v191
	v_cvt_f32_f16_sdwa v133, v191 dst_sel:DWORD dst_unused:UNUSED_PAD src0_sel:WORD_1
	v_cvt_f32_f16_e32 v136, v193
	v_cvt_f32_f16_sdwa v137, v193 dst_sel:DWORD dst_unused:UNUSED_PAD src0_sel:WORD_1
	v_pk_fma_f32 v[122:123], v[130:131], s[18:19], v[122:123] op_sel_hi:[1,0,1]
	v_pk_fma_f32 v[124:125], v[132:133], s[18:19], v[124:125] op_sel_hi:[1,0,1]
	v_mov_b32_e32 v132, v122
	v_pk_fma_f32 v[130:131], v[136:137], s[18:19], v[120:121] op_sel_hi:[1,0,1]
	v_pk_fma_f32 v[120:121], v[134:135], s[18:19], v[118:119] op_sel_hi:[1,0,1]
	v_pk_mov_b32 v[118:119], v[122:123], v[124:125] op_sel:[1,0]
	v_mov_b32_e32 v133, v125
	v_pk_add_f32 v[132:133], v[118:119], v[132:133]
	v_mul_f32_e32 v118, v122, v122
	v_pk_fma_f32 v[134:135], v[122:123], v[122:123], v[118:119] op_sel_hi:[1,1,0]
	v_mul_f32_e32 v118, v124, v124
	v_pk_fma_f32 v[136:137], v[124:125], v[124:125], v[118:119] op_sel_hi:[1,1,0]
	v_mul_f32_e32 v118, v130, v130
	v_add_f32_e32 v202, v120, v121
	v_mul_f32_e32 v197, v120, v120
	v_mul_f32_e32 v185, v121, v121
	v_pk_fma_f32 v[190:191], v[130:131], v[130:131], v[118:119] op_sel_hi:[1,1,0]
	v_cvt_pk_f16_f32 v118, v122, v123
	v_cvt_pk_f16_f32 v119, v124, v125
	v_cvt_pk_f16_f32 v120, v120, v121
	v_cvt_pk_f16_f32 v121, v130, v131
	global_store_dwordx4 v[194:195], v[118:121], off offset:256
	v_mul_f32_e32 v203, v186, v186
	v_mov_b32_e32 v200, v130
	v_pk_add_f32 v[118:119], v[132:133], v[132:133] op_sel:[0,1] op_sel_hi:[1,0]
	v_mov_b32_e32 v198, v131
	v_mov_b32_e32 v119, v1
	v_pk_add_f32 v[122:123], v[188:189], v[188:189] op_sel:[0,1] op_sel_hi:[1,0]
	v_pk_add_f32 v[118:119], v[202:203], v[118:119]
	v_pk_add_f32 v[120:121], v[200:201], v[198:199]
	v_mov_b32_e32 v134, v186
	v_mov_b32_e32 v136, v187
	v_mov_b32_e32 v123, v185
	v_pk_add_f32 v[118:119], v[118:119], v[120:121]
	v_pk_add_f32 v[120:121], v[134:135], v[136:137]
	v_pk_add_f32 v[122:123], v[196:197], v[122:123]
	v_mov_b32_e32 v1, v191
	v_pk_add_f32 v[120:121], v[122:123], v[120:121]
	s_nop 0
	v_pk_add_f32 v[120:121], v[120:121], v[0:1]
	s_nop 0
	v_pk_add_f32 v[118:119], v[118:119], v[120:121]
	ds_bpermute_b32 v120, v184, v118
	ds_bpermute_b32 v121, v184, v119
	s_waitcnt lgkmcnt(0)
	v_pk_add_f32 v[118:119], v[118:119], v[120:121]
	ds_bpermute_b32 v120, v183, v118
	ds_bpermute_b32 v121, v183, v119
	s_and_saveexec_b64 s[22:23], s[36:37]
	s_cbranch_execz .LBB0_829
	s_waitcnt lgkmcnt(0)
	v_pk_add_f32 v[118:119], v[118:119], v[120:121]
	v_lshlrev_b64 v[120:121], 7, v[170:171]
	v_lshl_add_u64 v[120:121], s[0:1], 0, v[120:121]
	v_lshl_add_u64 v[120:121], s[82:83], 3, v[120:121]
	s_lshl_b32 s58, s72, 3
	v_lshl_add_u64 v[120:121], v[120:121], 0, s[58:59]
	global_store_dwordx2 v[120:121], v[118:119], off
; #define PG8_LAS __attribute__((address_space(3)))
;     __device__ __forceinline__ void operator()(const f32x4 (&acc)[2][2][4][2], const Unit& u, int ui, int wr, int wc, int fr, int fq) const {
;     ...
;             for (int m = 0; m < 4; ++m) { const int row = row0 + ai * HALF + m * 16; const size_t off = (size_t)row * ldc + col0;
;                 float mu = 0.f, rs = 1.f; if (FOLD) { const f32x2_t ms = ((const PG8_LAS f32x2_t*)tb)[pslot + ai * HALF + wr * 64 + m * 16 + fr]; mu = ms.x; rs = ms.y; }
;                 float ssum = 0.f, ssq = 0.f;
; #pragma unroll
;                 for (int bj = 0; bj < 2; ++bj) { f32x4 v0 = acc[ai][bj][m][0], v1 = acc[ai][bj][m][1];
;                     if (FOLD && MODE != 2) { v0 = (v0 - mu * cv[bj][0]) * rs + bv[bj][0]; v1 = (v1 - mu * cv[bj][1]) * rs + bv[bj][1]; }
;                     if (MODE == 0) { v0 = v0 * sc; v1 = v1 * sc; }
;                     if (MODE == 1) { v0 = __builtin_elementwise_max(v0, (f32x4){0.f, 0.f, 0.f, 0.f}); v1 = __builtin_elementwise_max(v1, (f32x4){0.f, 0.f, 0.f, 0.f}); v0 = v0 * v0; v1 = v1 * v1; }
;                     if (MODE == 2) { const bf16x8 r = rr[m][bj];
;                         f32x4 h0 = (f32x4){(float)r[0], (float)r[1], (float)r[2], (float)r[3]}, h1 = (f32x4){(float)r[4], (float)r[5], (float)r[6], (float)r[7]};
;                         if (FOLD) { h0 = (h0 - mu) * rs * cv[bj][0] + bv[bj][0]; h1 = (h1 - mu) * rs * cv[bj][1] + bv[bj][1]; }
;                         v0 = v0 + alpha * h0; v1 = v1 + alpha * h1;
;                         ssum += (v0[0] + v0[1]) + (v0[2] + v0[3]) + (v1[0] + v1[1]) + (v1[2] + v1[3]);
;                         ssq += (v0[0] * v0[0] + v0[1] * v0[1]) + (v0[2] * v0[2] + v0[3] * v0[3]) + (v1[0] * v1[0] + v1[1] * v1[1]) + (v1[2] * v1[2] + v1[3] * v1[3]); }
;                     u32x4 w; w.x = pk2h(v0[0], v0[1]); w.y = pk2h(v0[2], v0[3]); w.z = pk2h(v1[0], v1[1]); w.w = pk2h(v1[2], v1[3]);
;                     if (MODE == 0 && hm) { const int cc = col0 + bj * HALF; *(u32x4*)(base + ((size_t)(row >> 11) * 16 + (cc >> 6)) * 131072 + (size_t)(row & 2047) * 64 + (cc & 63)) = w; }
;                     else *(u32x4*)(base + off + bj * HALF) = w; }
;                 if (MODE == 2) { ssum += __shfl_xor(ssum, 16); ssq += __shfl_xor(ssq, 16); ssum += __shfl_xor(ssum, 32); ssq += __shfl_xor(ssq, 32);
.LBB0_829:
	s_or_b64 exec, exec, s[22:23]
	s_waitcnt vmcnt(6)
	s_waitcnt lgkmcnt(0)
	v_cvt_f32_f16_sdwa v121, v154 dst_sel:DWORD dst_unused:UNUSED_PAD src0_sel:WORD_1
	v_cvt_f32_f16_e32 v120, v154
	v_cvt_f32_f16_sdwa v123, v155 dst_sel:DWORD dst_unused:UNUSED_PAD src0_sel:WORD_1
	v_cvt_f32_f16_e32 v122, v155
	v_cvt_f32_f16_sdwa v125, v156 dst_sel:DWORD dst_unused:UNUSED_PAD src0_sel:WORD_1
	v_cvt_f32_f16_e32 v124, v156
	v_cvt_f32_f16_sdwa v131, v157 dst_sel:DWORD dst_unused:UNUSED_PAD src0_sel:WORD_1
	v_cvt_f32_f16_e32 v130, v157
	v_pk_fma_f32 v[116:117], v[122:123], s[18:19], v[116:117] op_sel_hi:[1,0,1]
	v_pk_fma_f32 v[114:115], v[120:121], s[18:19], v[114:115] op_sel_hi:[1,0,1]
	v_mov_b32_e32 v123, v117
	v_pk_fma_f32 v[120:121], v[130:131], s[18:19], v[112:113] op_sel_hi:[1,0,1]
	v_pk_fma_f32 v[112:113], v[124:125], s[18:19], v[110:111] op_sel_hi:[1,0,1]
	v_pk_mov_b32 v[110:111], v[114:115], v[116:117] op_sel:[1,0]
	v_mov_b32_e32 v122, v114
	v_pk_add_f32 v[122:123], v[110:111], v[122:123]
	v_pk_mul_f32 v[110:111], v[116:117], v[116:117]
	v_pk_mul_f32 v[130:131], v[114:115], v[114:115]
	v_lshlrev_b64 v[118:119], 10, v[178:179]
	v_pk_mov_b32 v[132:133], v[130:131], v[110:111] op_sel:[1,0]
	v_mov_b32_e32 v131, v111
	v_pk_add_f32 v[110:111], v[132:133], v[130:131]
	v_lshl_add_u64 v[118:119], v[118:119], 1, v[168:169]
	v_pk_add_f32 v[130:131], v[110:111], v[110:111] op_sel_hi:[0,1]
	v_mul_f32_e32 v110, v112, v112
	v_add_f32_e32 v124, v112, v113
	v_pk_fma_f32 v[132:133], v[112:113], v[112:113], v[110:111] op_sel_hi:[1,1,0]
	v_cvt_pk_f16_f32 v110, v114, v115
	v_cvt_pk_f16_f32 v111, v116, v117
	v_cvt_pk_f16_f32 v112, v112, v113
	v_cvt_pk_f16_f32 v113, v120, v121
	global_store_dwordx4 v[118:119], v[110:113], off
	v_cvt_f32_f16_sdwa v115, v152 dst_sel:DWORD dst_unused:UNUSED_PAD src0_sel:WORD_1
	v_cvt_f32_f16_e32 v114, v152
	v_cvt_f32_f16_sdwa v111, v150 dst_sel:DWORD dst_unused:UNUSED_PAD src0_sel:WORD_1
	v_cvt_f32_f16_e32 v110, v150
	v_cvt_f32_f16_sdwa v113, v151 dst_sel:DWORD dst_unused:UNUSED_PAD src0_sel:WORD_1
	v_cvt_f32_f16_e32 v112, v151
	v_cvt_f32_f16_sdwa v117, v153 dst_sel:DWORD dst_unused:UNUSED_PAD src0_sel:WORD_1
	v_cvt_f32_f16_e32 v116, v153
	v_pk_fma_f32 v[106:107], v[110:111], s[18:19], v[106:107] op_sel_hi:[1,0,1]
	v_pk_fma_f32 v[108:109], v[112:113], s[18:19], v[108:109] op_sel_hi:[1,0,1]
	v_mov_b32_e32 v112, v106
	v_pk_fma_f32 v[110:111], v[116:117], s[18:19], v[104:105] op_sel_hi:[1,0,1]
	v_pk_fma_f32 v[104:105], v[114:115], s[18:19], v[102:103] op_sel_hi:[1,0,1]
	v_pk_mov_b32 v[102:103], v[106:107], v[108:109] op_sel:[1,0]
	v_mov_b32_e32 v113, v109
	v_pk_add_f32 v[112:113], v[102:103], v[112:113]
	v_mul_f32_e32 v102, v106, v106
	v_pk_fma_f32 v[114:115], v[106:107], v[106:107], v[102:103] op_sel_hi:[1,1,0]
	v_mul_f32_e32 v102, v108, v108
	v_pk_fma_f32 v[116:117], v[108:109], v[108:109], v[102:103] op_sel_hi:[1,1,0]
	v_mul_f32_e32 v102, v110, v110
	v_add_f32_e32 v134, v104, v105
	v_mul_f32_e32 v125, v104, v104
	v_mul_f32_e32 v150, v105, v105
	v_pk_fma_f32 v[136:137], v[110:111], v[110:111], v[102:103] op_sel_hi:[1,1,0]
	v_cvt_pk_f16_f32 v102, v106, v107
	v_cvt_pk_f16_f32 v103, v108, v109
	v_cvt_pk_f16_f32 v104, v104, v105
	v_cvt_pk_f16_f32 v105, v110, v111
	v_mul_f32_e32 v1, v121, v121
	global_store_dwordx4 v[118:119], v[102:105], off offset:256
	v_mul_f32_e32 v135, v120, v120
	v_mov_b32_e32 v132, v110
	v_pk_add_f32 v[102:103], v[112:113], v[112:113] op_sel:[0,1] op_sel_hi:[1,0]
	v_mov_b32_e32 v130, v111
	v_mov_b32_e32 v103, v1
	v_pk_add_f32 v[106:107], v[122:123], v[122:123] op_sel:[0,1] op_sel_hi:[1,0]
	v_pk_add_f32 v[102:103], v[134:135], v[102:103]
	v_pk_add_f32 v[104:105], v[132:133], v[130:131]
	v_mov_b32_e32 v114, v120
	v_mov_b32_e32 v116, v121
	v_mov_b32_e32 v107, v150
	v_pk_add_f32 v[102:103], v[102:103], v[104:105]
	v_pk_add_f32 v[104:105], v[114:115], v[116:117]
	v_pk_add_f32 v[106:107], v[124:125], v[106:107]
	v_mov_b32_e32 v1, v137
	v_pk_add_f32 v[104:105], v[106:107], v[104:105]
	s_nop 0
	v_pk_add_f32 v[104:105], v[104:105], v[0:1]
	s_nop 0
	v_pk_add_f32 v[102:103], v[102:103], v[104:105]
	ds_bpermute_b32 v104, v184, v102
	ds_bpermute_b32 v105, v184, v103
	s_waitcnt lgkmcnt(0)
	v_pk_add_f32 v[102:103], v[102:103], v[104:105]
	ds_bpermute_b32 v104, v183, v102
	ds_bpermute_b32 v105, v183, v103
	s_and_saveexec_b64 s[22:23], s[36:37]
	s_cbranch_execz .LBB0_831
	s_waitcnt lgkmcnt(0)
	v_pk_add_f32 v[102:103], v[102:103], v[104:105]
	v_lshlrev_b64 v[104:105], 7, v[178:179]
	v_lshl_add_u64 v[104:105], s[0:1], 0, v[104:105]
	v_lshl_add_u64 v[104:105], s[82:83], 3, v[104:105]
	s_lshl_b32 s58, s72, 3
	v_lshl_add_u64 v[104:105], v[104:105], 0, s[58:59]
	global_store_dwordx2 v[104:105], v[102:103], off
; #define PG8_LAS __attribute__((address_space(3)))
;     __device__ __forceinline__ void operator()(const f32x4 (&acc)[2][2][4][2], const Unit& u, int ui, int wr, int wc, int fr, int fq) const {
;     ...
;             for (int m = 0; m < 4; ++m) { const int row = row0 + ai * HALF + m * 16; const size_t off = (size_t)row * ldc + col0;
;                 float mu = 0.f, rs = 1.f; if (FOLD) { const f32x2_t ms = ((const PG8_LAS f32x2_t*)tb)[pslot + ai * HALF + wr * 64 + m * 16 + fr]; mu = ms.x; rs = ms.y; }
;                 float ssum = 0.f, ssq = 0.f;
; #pragma unroll
;                 for (int bj = 0; bj < 2; ++bj) { f32x4 v0 = acc[ai][bj][m][0], v1 = acc[ai][bj][m][1];
;                     if (FOLD && MODE != 2) { v0 = (v0 - mu * cv[bj][0]) * rs + bv[bj][0]; v1 = (v1 - mu * cv[bj][1]) * rs + bv[bj][1]; }
;                     if (MODE == 0) { v0 = v0 * sc; v1 = v1 * sc; }
;                     if (MODE == 1) { v0 = __builtin_elementwise_max(v0, (f32x4){0.f, 0.f, 0.f, 0.f}); v1 = __builtin_elementwise_max(v1, (f32x4){0.f, 0.f, 0.f, 0.f}); v0 = v0 * v0; v1 = v1 * v1; }
;                     if (MODE == 2) { const bf16x8 r = rr[m][bj];
;                         f32x4 h0 = (f32x4){(float)r[0], (float)r[1], (float)r[2], (float)r[3]}, h1 = (f32x4){(float)r[4], (float)r[5], (float)r[6], (float)r[7]};
;                         if (FOLD) { h0 = (h0 - mu) * rs * cv[bj][0] + bv[bj][0]; h1 = (h1 - mu) * rs * cv[bj][1] + bv[bj][1]; }
;                         v0 = v0 + alpha * h0; v1 = v1 + alpha * h1;
;                         ssum += (v0[0] + v0[1]) + (v0[2] + v0[3]) + (v1[0] + v1[1]) + (v1[2] + v1[3]);
;                         ssq += (v0[0] * v0[0] + v0[1] * v0[1]) + (v0[2] * v0[2] + v0[3] * v0[3]) + (v1[0] * v1[0] + v1[1] * v1[1]) + (v1[2] * v1[2] + v1[3] * v1[3]); }
;                     u32x4 w; w.x = pk2h(v0[0], v0[1]); w.y = pk2h(v0[2], v0[3]); w.z = pk2h(v1[0], v1[1]); w.w = pk2h(v1[2], v1[3]);
;                     if (MODE == 0 && hm) { const int cc = col0 + bj * HALF; *(u32x4*)(base + ((size_t)(row >> 11) * 16 + (cc >> 6)) * 131072 + (size_t)(row & 2047) * 64 + (cc & 63)) = w; }
;                     else *(u32x4*)(base + off + bj * HALF) = w; }
;                 if (MODE == 2) { ssum += __shfl_xor(ssum, 16); ssq += __shfl_xor(ssq, 16); ssum += __shfl_xor(ssum, 32); ssq += __shfl_xor(ssq, 32);
.LBB0_831:
	s_or_b64 exec, exec, s[22:23]
	s_waitcnt vmcnt(6)
	s_waitcnt lgkmcnt(0)
	v_cvt_f32_f16_sdwa v105, v146 dst_sel:DWORD dst_unused:UNUSED_PAD src0_sel:WORD_1
	v_cvt_f32_f16_e32 v104, v146
	v_cvt_f32_f16_sdwa v107, v147 dst_sel:DWORD dst_unused:UNUSED_PAD src0_sel:WORD_1
	v_cvt_f32_f16_e32 v106, v147
	v_cvt_f32_f16_sdwa v109, v148 dst_sel:DWORD dst_unused:UNUSED_PAD src0_sel:WORD_1
	v_cvt_f32_f16_e32 v108, v148
	v_cvt_f32_f16_sdwa v111, v149 dst_sel:DWORD dst_unused:UNUSED_PAD src0_sel:WORD_1
	v_cvt_f32_f16_e32 v110, v149
	v_pk_fma_f32 v[100:101], v[106:107], s[18:19], v[100:101] op_sel_hi:[1,0,1]
	v_pk_fma_f32 v[98:99], v[104:105], s[18:19], v[98:99] op_sel_hi:[1,0,1]
	v_mov_b32_e32 v107, v101
	v_pk_fma_f32 v[104:105], v[110:111], s[18:19], v[96:97] op_sel_hi:[1,0,1]
	v_pk_fma_f32 v[96:97], v[108:109], s[18:19], v[94:95] op_sel_hi:[1,0,1]
	v_pk_mov_b32 v[94:95], v[98:99], v[100:101] op_sel:[1,0]
	v_mov_b32_e32 v106, v98
	v_pk_add_f32 v[106:107], v[94:95], v[106:107]
	v_pk_mul_f32 v[94:95], v[100:101], v[100:101]
	v_pk_mul_f32 v[110:111], v[98:99], v[98:99]
	v_lshlrev_b64 v[102:103], 10, v[176:177]
	v_pk_mov_b32 v[112:113], v[110:111], v[94:95] op_sel:[1,0]
	v_mov_b32_e32 v111, v95
	v_pk_add_f32 v[94:95], v[112:113], v[110:111]
	v_lshl_add_u64 v[102:103], v[102:103], 1, v[168:169]
	v_pk_add_f32 v[110:111], v[94:95], v[94:95] op_sel_hi:[0,1]
	v_mul_f32_e32 v94, v96, v96
	v_add_f32_e32 v108, v96, v97
	v_pk_fma_f32 v[112:113], v[96:97], v[96:97], v[94:95] op_sel_hi:[1,1,0]
	v_cvt_pk_f16_f32 v94, v98, v99
	v_cvt_pk_f16_f32 v95, v100, v101
	v_cvt_pk_f16_f32 v96, v96, v97
	v_cvt_pk_f16_f32 v97, v104, v105
	global_store_dwordx4 v[102:103], v[94:97], off
	v_cvt_f32_f16_sdwa v99, v144 dst_sel:DWORD dst_unused:UNUSED_PAD src0_sel:WORD_1
	v_cvt_f32_f16_e32 v98, v144
	v_cvt_f32_f16_sdwa v95, v142 dst_sel:DWORD dst_unused:UNUSED_PAD src0_sel:WORD_1
	v_cvt_f32_f16_e32 v94, v142
	v_cvt_f32_f16_sdwa v97, v143 dst_sel:DWORD dst_unused:UNUSED_PAD src0_sel:WORD_1
	v_cvt_f32_f16_e32 v96, v143
	v_cvt_f32_f16_sdwa v101, v145 dst_sel:DWORD dst_unused:UNUSED_PAD src0_sel:WORD_1
	v_cvt_f32_f16_e32 v100, v145
	v_pk_fma_f32 v[90:91], v[94:95], s[18:19], v[90:91] op_sel_hi:[1,0,1]
	v_pk_fma_f32 v[92:93], v[96:97], s[18:19], v[92:93] op_sel_hi:[1,0,1]
	v_mov_b32_e32 v96, v90
	v_pk_fma_f32 v[94:95], v[100:101], s[18:19], v[88:89] op_sel_hi:[1,0,1]
	v_pk_fma_f32 v[88:89], v[98:99], s[18:19], v[86:87] op_sel_hi:[1,0,1]
	v_pk_mov_b32 v[86:87], v[90:91], v[92:93] op_sel:[1,0]
	v_mov_b32_e32 v97, v93
	v_pk_add_f32 v[96:97], v[86:87], v[96:97]
	v_mul_f32_e32 v86, v90, v90
	v_pk_fma_f32 v[98:99], v[90:91], v[90:91], v[86:87] op_sel_hi:[1,1,0]
	v_mul_f32_e32 v86, v92, v92
	v_pk_fma_f32 v[100:101], v[92:93], v[92:93], v[86:87] op_sel_hi:[1,1,0]
	v_mul_f32_e32 v86, v94, v94
	v_add_f32_e32 v114, v88, v89
	v_mul_f32_e32 v109, v88, v88
	v_mul_f32_e32 v118, v89, v89
	v_pk_fma_f32 v[116:117], v[94:95], v[94:95], v[86:87] op_sel_hi:[1,1,0]
	v_cvt_pk_f16_f32 v86, v90, v91
	v_cvt_pk_f16_f32 v87, v92, v93
	v_cvt_pk_f16_f32 v88, v88, v89
	v_cvt_pk_f16_f32 v89, v94, v95
	v_mul_f32_e32 v1, v105, v105
	global_store_dwordx4 v[102:103], v[86:89], off offset:256
	v_mul_f32_e32 v115, v104, v104
	v_mov_b32_e32 v112, v94
	v_pk_add_f32 v[86:87], v[96:97], v[96:97] op_sel:[0,1] op_sel_hi:[1,0]
	v_mov_b32_e32 v110, v95
	v_mov_b32_e32 v87, v1
	v_pk_add_f32 v[90:91], v[106:107], v[106:107] op_sel:[0,1] op_sel_hi:[1,0]
	v_pk_add_f32 v[86:87], v[114:115], v[86:87]
	v_pk_add_f32 v[88:89], v[112:113], v[110:111]
	v_mov_b32_e32 v98, v104
	v_mov_b32_e32 v100, v105
	v_mov_b32_e32 v91, v118
	v_pk_add_f32 v[86:87], v[86:87], v[88:89]
	v_pk_add_f32 v[88:89], v[98:99], v[100:101]
	v_pk_add_f32 v[90:91], v[108:109], v[90:91]
	v_mov_b32_e32 v1, v117
	v_pk_add_f32 v[88:89], v[90:91], v[88:89]
	s_nop 0
	v_pk_add_f32 v[88:89], v[88:89], v[0:1]
	s_nop 0
	v_pk_add_f32 v[86:87], v[86:87], v[88:89]
	ds_bpermute_b32 v88, v184, v86
	ds_bpermute_b32 v89, v184, v87
	s_waitcnt lgkmcnt(0)
	v_pk_add_f32 v[86:87], v[86:87], v[88:89]
	ds_bpermute_b32 v88, v183, v86
	ds_bpermute_b32 v89, v183, v87
	s_and_saveexec_b64 s[22:23], s[36:37]
	v_readlane_b32 s54, v255, 25
	v_readlane_b32 s55, v255, 26
	s_cbranch_execz .LBB0_833
	s_waitcnt lgkmcnt(0)
	v_pk_add_f32 v[86:87], v[86:87], v[88:89]
	v_lshlrev_b64 v[88:89], 7, v[176:177]
	v_lshl_add_u64 v[88:89], s[0:1], 0, v[88:89]
	v_lshl_add_u64 v[88:89], s[82:83], 3, v[88:89]
	s_lshl_b32 s58, s72, 3
	v_lshl_add_u64 v[88:89], v[88:89], 0, s[58:59]
	global_store_dwordx2 v[88:89], v[86:87], off
; #define PG8_LAS __attribute__((address_space(3)))
;     __device__ __forceinline__ void operator()(const f32x4 (&acc)[2][2][4][2], const Unit& u, int ui, int wr, int wc, int fr, int fq) const {
;     ...
;             for (int m = 0; m < 4; ++m) { const int row = row0 + ai * HALF + m * 16; const size_t off = (size_t)row * ldc + col0;
;                 float mu = 0.f, rs = 1.f; if (FOLD) { const f32x2_t ms = ((const PG8_LAS f32x2_t*)tb)[pslot + ai * HALF + wr * 64 + m * 16 + fr]; mu = ms.x; rs = ms.y; }
;                 float ssum = 0.f, ssq = 0.f;
; #pragma unroll
;                 for (int bj = 0; bj < 2; ++bj) { f32x4 v0 = acc[ai][bj][m][0], v1 = acc[ai][bj][m][1];
;                     if (FOLD && MODE != 2) { v0 = (v0 - mu * cv[bj][0]) * rs + bv[bj][0]; v1 = (v1 - mu * cv[bj][1]) * rs + bv[bj][1]; }
;                     if (MODE == 0) { v0 = v0 * sc; v1 = v1 * sc; }
;                     if (MODE == 1) { v0 = __builtin_elementwise_max(v0, (f32x4){0.f, 0.f, 0.f, 0.f}); v1 = __builtin_elementwise_max(v1, (f32x4){0.f, 0.f, 0.f, 0.f}); v0 = v0 * v0; v1 = v1 * v1; }
;                     if (MODE == 2) { const bf16x8 r = rr[m][bj];
;                         f32x4 h0 = (f32x4){(float)r[0], (float)r[1], (float)r[2], (float)r[3]}, h1 = (f32x4){(float)r[4], (float)r[5], (float)r[6], (float)r[7]};
;                         if (FOLD) { h0 = (h0 - mu) * rs * cv[bj][0] + bv[bj][0]; h1 = (h1 - mu) * rs * cv[bj][1] + bv[bj][1]; }
;                         v0 = v0 + alpha * h0; v1 = v1 + alpha * h1;
;                         ssum += (v0[0] + v0[1]) + (v0[2] + v0[3]) + (v1[0] + v1[1]) + (v1[2] + v1[3]);
;                         ssq += (v0[0] * v0[0] + v0[1] * v0[1]) + (v0[2] * v0[2] + v0[3] * v0[3]) + (v1[0] * v1[0] + v1[1] * v1[1]) + (v1[2] * v1[2] + v1[3] * v1[3]); }
;                     u32x4 w; w.x = pk2h(v0[0], v0[1]); w.y = pk2h(v0[2], v0[3]); w.z = pk2h(v1[0], v1[1]); w.w = pk2h(v1[2], v1[3]);
;                     if (MODE == 0 && hm) { const int cc = col0 + bj * HALF; *(u32x4*)(base + ((size_t)(row >> 11) * 16 + (cc >> 6)) * 131072 + (size_t)(row & 2047) * 64 + (cc & 63)) = w; }
;                     else *(u32x4*)(base + off + bj * HALF) = w; }
;                 if (MODE == 2) { ssum += __shfl_xor(ssum, 16); ssq += __shfl_xor(ssq, 16); ssum += __shfl_xor(ssum, 32); ssq += __shfl_xor(ssq, 32);
.LBB0_833:
	s_or_b64 exec, exec, s[22:23]
	s_waitcnt vmcnt(6)
	s_waitcnt lgkmcnt(0)
	v_cvt_f32_f16_sdwa v89, v138 dst_sel:DWORD dst_unused:UNUSED_PAD src0_sel:WORD_1
	v_cvt_f32_f16_e32 v88, v138
	v_cvt_f32_f16_sdwa v91, v139 dst_sel:DWORD dst_unused:UNUSED_PAD src0_sel:WORD_1
	v_cvt_f32_f16_e32 v90, v139
	v_cvt_f32_f16_sdwa v93, v140 dst_sel:DWORD dst_unused:UNUSED_PAD src0_sel:WORD_1
	v_cvt_f32_f16_e32 v92, v140
	v_cvt_f32_f16_sdwa v95, v141 dst_sel:DWORD dst_unused:UNUSED_PAD src0_sel:WORD_1
	v_cvt_f32_f16_e32 v94, v141
	v_pk_fma_f32 v[84:85], v[90:91], s[18:19], v[84:85] op_sel_hi:[1,0,1]
	v_pk_fma_f32 v[82:83], v[88:89], s[18:19], v[82:83] op_sel_hi:[1,0,1]
	v_mov_b32_e32 v91, v85
	v_pk_fma_f32 v[88:89], v[94:95], s[18:19], v[80:81] op_sel_hi:[1,0,1]
	v_pk_fma_f32 v[80:81], v[92:93], s[18:19], v[78:79] op_sel_hi:[1,0,1]
	v_pk_mov_b32 v[78:79], v[82:83], v[84:85] op_sel:[1,0]
	v_mov_b32_e32 v90, v82
	v_pk_add_f32 v[90:91], v[78:79], v[90:91]
	v_pk_mul_f32 v[78:79], v[84:85], v[84:85]
	v_pk_mul_f32 v[94:95], v[82:83], v[82:83]
	v_lshlrev_b64 v[86:87], 10, v[174:175]
	v_pk_mov_b32 v[96:97], v[94:95], v[78:79] op_sel:[1,0]
	v_mov_b32_e32 v95, v79
	v_pk_add_f32 v[78:79], v[96:97], v[94:95]
	v_lshl_add_u64 v[86:87], v[86:87], 1, v[168:169]
	v_pk_add_f32 v[94:95], v[78:79], v[78:79] op_sel_hi:[0,1]
	v_mul_f32_e32 v78, v80, v80
	v_add_f32_e32 v92, v80, v81
	v_pk_fma_f32 v[96:97], v[80:81], v[80:81], v[78:79] op_sel_hi:[1,1,0]
	v_cvt_pk_f16_f32 v78, v82, v83
	v_cvt_pk_f16_f32 v79, v84, v85
	v_cvt_pk_f16_f32 v80, v80, v81
	v_cvt_pk_f16_f32 v81, v88, v89
	global_store_dwordx4 v[86:87], v[78:81], off
	v_cvt_f32_f16_sdwa v83, v128 dst_sel:DWORD dst_unused:UNUSED_PAD src0_sel:WORD_1
	v_cvt_f32_f16_e32 v82, v128
	v_cvt_f32_f16_sdwa v79, v126 dst_sel:DWORD dst_unused:UNUSED_PAD src0_sel:WORD_1
	v_cvt_f32_f16_e32 v78, v126
	v_cvt_f32_f16_sdwa v81, v127 dst_sel:DWORD dst_unused:UNUSED_PAD src0_sel:WORD_1
	v_cvt_f32_f16_e32 v80, v127
	v_cvt_f32_f16_sdwa v85, v129 dst_sel:DWORD dst_unused:UNUSED_PAD src0_sel:WORD_1
	v_cvt_f32_f16_e32 v84, v129
	v_pk_fma_f32 v[74:75], v[78:79], s[18:19], v[74:75] op_sel_hi:[1,0,1]
	v_pk_fma_f32 v[76:77], v[80:81], s[18:19], v[76:77] op_sel_hi:[1,0,1]
	v_mov_b32_e32 v80, v74
	v_pk_fma_f32 v[78:79], v[84:85], s[18:19], v[72:73] op_sel_hi:[1,0,1]
	v_pk_fma_f32 v[72:73], v[82:83], s[18:19], v[70:71] op_sel_hi:[1,0,1]
	v_pk_mov_b32 v[70:71], v[74:75], v[76:77] op_sel:[1,0]
	v_mov_b32_e32 v81, v77
	v_pk_add_f32 v[80:81], v[70:71], v[80:81]
	v_mul_f32_e32 v70, v74, v74
	v_pk_fma_f32 v[82:83], v[74:75], v[74:75], v[70:71] op_sel_hi:[1,1,0]
	v_mul_f32_e32 v70, v76, v76
	v_pk_fma_f32 v[84:85], v[76:77], v[76:77], v[70:71] op_sel_hi:[1,1,0]
	v_mul_f32_e32 v70, v78, v78
	v_add_f32_e32 v98, v72, v73
	v_mul_f32_e32 v93, v72, v72
	v_mul_f32_e32 v102, v73, v73
	v_pk_fma_f32 v[100:101], v[78:79], v[78:79], v[70:71] op_sel_hi:[1,1,0]
	v_cvt_pk_f16_f32 v70, v74, v75
	v_cvt_pk_f16_f32 v71, v76, v77
	v_cvt_pk_f16_f32 v72, v72, v73
	v_cvt_pk_f16_f32 v73, v78, v79
	v_mul_f32_e32 v1, v89, v89
	global_store_dwordx4 v[86:87], v[70:73], off offset:256
	v_mul_f32_e32 v99, v88, v88
	v_mov_b32_e32 v96, v78
	v_pk_add_f32 v[70:71], v[80:81], v[80:81] op_sel:[0,1] op_sel_hi:[1,0]
	v_mov_b32_e32 v94, v79
	v_mov_b32_e32 v71, v1
	v_pk_add_f32 v[74:75], v[90:91], v[90:91] op_sel:[0,1] op_sel_hi:[1,0]
	v_pk_add_f32 v[70:71], v[98:99], v[70:71]
	v_pk_add_f32 v[72:73], v[96:97], v[94:95]
	v_mov_b32_e32 v82, v88
	v_mov_b32_e32 v84, v89
	v_mov_b32_e32 v75, v102
	v_pk_add_f32 v[70:71], v[70:71], v[72:73]
	v_pk_add_f32 v[72:73], v[82:83], v[84:85]
	v_pk_add_f32 v[74:75], v[92:93], v[74:75]
	v_mov_b32_e32 v1, v101
	v_pk_add_f32 v[72:73], v[74:75], v[72:73]
	s_nop 0
	v_pk_add_f32 v[72:73], v[72:73], v[0:1]
	s_nop 0
	v_pk_add_f32 v[70:71], v[70:71], v[72:73]
	ds_bpermute_b32 v72, v184, v70
	ds_bpermute_b32 v73, v184, v71
	s_waitcnt lgkmcnt(0)
	v_pk_add_f32 v[70:71], v[70:71], v[72:73]
	ds_bpermute_b32 v72, v183, v70
	ds_bpermute_b32 v73, v183, v71
	s_and_saveexec_b64 s[22:23], s[36:37]
	s_cbranch_execz .LBB0_835
	s_waitcnt lgkmcnt(0)
	v_pk_add_f32 v[70:71], v[70:71], v[72:73]
	v_lshlrev_b64 v[72:73], 7, v[174:175]
	v_lshl_add_u64 v[72:73], s[0:1], 0, v[72:73]
	v_lshl_add_u64 v[72:73], s[82:83], 3, v[72:73]
	s_lshl_b32 s58, s72, 3
	v_lshl_add_u64 v[72:73], v[72:73], 0, s[58:59]
	global_store_dwordx2 v[72:73], v[70:71], off

;     __device__ __forceinline__ void operator()(const f32x4 (&acc)[2][2][4][2], const Unit& u, int ui, int wr, int wc, int fr, int fq) const {
;     ...
;         if (FOLD) { const PG8_LAS int* sl = (const PG8_LAS int*)(tb + 16384); pslot = sl[ui] * 256; const int cslot = sl[16 + ui] * 256 + wc * 32 + 8 * fq;
;             const PG8_LAS float* csl = (const PG8_LAS float*)(tb + 8192); const PG8_LAS float* bwl = (const PG8_LAS float*)(tb + 12288);
; #pragma unroll
;             for (int bj = 0; bj < 2; ++bj)
; #pragma unroll
;                 for (int n = 0; n < 2; ++n) { cv[bj][n] = *(const PG8_LAS f32x4*)(csl + cslot + bj * HALF + 4 * n); bv[bj][n] = *(const PG8_LAS f32x4*)(bwl + cslot + bj * HALF + 4 * n); } }
; #pragma unroll
;         for (int ai = 0; ai < 2; ++ai) {
;         bf16x8 rr[4][2];
;         if (MODE == 2) {
; #pragma unroll
;             for (int m = 0; m < 4; ++m)
; #pragma unroll
;                 for (int bj = 0; bj < 2; ++bj) rr[m][bj] = *(const bf16x8*)(R + (size_t)(row0 + ai * HALF + m * 16) * ldc + col0 + bj * HALF);
;             __builtin_amdgcn_sched_barrier(0); }
; #pragma unroll
;             for (int m = 0; m < 4; ++m) { const int row = row0 + ai * HALF + m * 16; const size_t off = (size_t)row * ldc + col0;
;                 float mu = 0.f, rs = 1.f; if (FOLD) { const f32x2_t ms = ((const PG8_LAS f32x2_t*)tb)[pslot + ai * HALF + wr * 64 + m * 16 + fr]; mu = ms.x; rs = ms.y; }
;                 float ssum = 0.f, ssq = 0.f;
; #pragma unroll
;                 for (int bj = 0; bj < 2; ++bj) { f32x4 v0 = acc[ai][bj][m][0], v1 = acc[ai][bj][m][1];
;                     if (FOLD && MODE != 2) { v0 = (v0 - mu * cv[bj][0]) * rs + bv[bj][0]; v1 = (v1 - mu * cv[bj][1]) * rs + bv[bj][1]; }
;                     if (MODE == 0) { v0 = v0 * sc; v1 = v1 * sc; }
;                     if (MODE == 1) { v0 = __builtin_elementwise_max(v0, (f32x4){0.f, 0.f, 0.f, 0.f}); v1 = __builtin_elementwise_max(v1, (f32x4){0.f, 0.f, 0.f, 0.f}); v0 = v0 * v0; v1 = v1 * v1; }
;                     if (MODE == 2) { const bf16x8 r = rr[m][bj];
;                         f32x4 h0 = (f32x4){(float)r[0], (float)r[1], (float)r[2], (float)r[3]}, h1 = (f32x4){(float)r[4], (float)r[5], (float)r[6], (float)r[7]};
;                         if (FOLD) { h0 = (h0 - mu) * rs * cv[bj][0] + bv[bj][0]; h1 = (h1 - mu) * rs * cv[bj][1] + bv[bj][1]; }
.LBB0_1137:
	v_lshl_or_b32 v66, s20, 8, v223
	v_lshl_add_u32 v202, s27, 8, v17
	v_ashrrev_i32_e32 v67, 31, v66
	v_lshlrev_b64 v[200:201], 1, v[66:67]
	v_ashrrev_i32_e32 v203, 31, v202
	v_lshl_add_u64 v[204:205], s[56:57], 0, v[200:201]
	v_lshlrev_b64 v[230:231], 11, v[202:203]
	v_or_b32_e32 v220, 16, v202
	v_lshl_add_u64 v[66:67], v[204:205], 0, v[230:231]
	v_ashrrev_i32_e32 v221, 31, v220
	global_load_dwordx4 v[208:211], v[66:67], off
	global_load_dwordx4 v[212:215], v[66:67], off offset:256
	v_lshlrev_b64 v[66:67], 11, v[220:221]
	v_or_b32_e32 v218, 32, v202
	v_lshl_add_u64 v[66:67], v[204:205], 0, v[66:67]
	v_ashrrev_i32_e32 v219, 31, v218
	global_load_dwordx4 v[186:189], v[66:67], off
	global_load_dwordx4 v[182:185], v[66:67], off offset:256
	v_lshlrev_b64 v[66:67], 11, v[218:219]
	v_or_b32_e32 v206, 48, v202
	v_lshl_add_u64 v[66:67], v[204:205], 0, v[66:67]
	v_ashrrev_i32_e32 v207, 31, v206
	global_load_dwordx4 v[178:181], v[66:67], off
	global_load_dwordx4 v[174:177], v[66:67], off offset:256
	v_lshlrev_b64 v[66:67], 11, v[206:207]
	v_lshl_add_u64 v[66:67], v[204:205], 0, v[66:67]
	global_load_dwordx4 v[170:173], v[66:67], off
	global_load_dwordx4 v[158:161], v[66:67], off offset:256
	s_lshl_b32 s12, s26, 2
	s_add_i32 s12, s12, 0
	s_add_i32 s12, s12, 0x24000
	v_mov_b32_e32 v1, s12
	ds_read2_b32 v[226:227], v1 offset1:16
	v_lshlrev_b32_e32 v1, 2, v223
	v_readlane_b32 s12, v254, 41
	v_readlane_b32 s13, v254, 42
	s_waitcnt lgkmcnt(0)
	v_lshl_or_b32 v1, v227, 10, v1
	v_add_u32_e32 v1, 0, v1
	v_add_u32_e32 v66, 0x22000, v1
	v_add_u32_e32 v1, 0x23000, v1
	ds_read_b128 v[94:97], v66
	ds_read_b128 v[86:89], v66 offset:16
	ds_read_b128 v[98:101], v1
	ds_read_b128 v[90:93], v1 offset:16
	ds_read_b128 v[78:81], v66 offset:512
	ds_read_b128 v[66:69], v66 offset:528
	ds_read_b128 v[82:85], v1 offset:512
	ds_read_b128 v[70:73], v1 offset:528
	v_and_b32_e32 v227, 64, v237
	v_lshlrev_b32_e32 v1, 11, v226
	v_xor_b32_e32 v226, 16, v237
	v_add_u32_e32 v228, 64, v227
	v_cmp_lt_i32_e32 vcc, v226, v228
	v_lshl_add_u64 v[200:201], s[12:13], 0, v[200:201]
	s_nop 0
	v_cndmask_b32_e32 v226, v237, v226, vcc
	v_lshlrev_b32_e32 v227, 2, v226
	v_xor_b32_e32 v226, 32, v237
	v_cmp_lt_i32_e32 vcc, v226, v228
	s_nop 1
	v_cndmask_b32_e32 v226, v237, v226, vcc
	s_lshl_b32 vcc_lo, s20, 2
	v_lshlrev_b32_e32 v226, 2, v226
	s_ashr_i32 vcc_hi, vcc_lo, 31
	v_add_u32_e32 v228, v224, v1
	ds_read_b64 v[232:233], v228
	s_waitcnt vmcnt(6)
	v_cvt_f32_f16_sdwa v1, v208 dst_sel:DWORD dst_unused:UNUSED_PAD src0_sel:WORD_1
	v_cvt_f32_f16_e32 v208, v208
	v_cvt_f32_f16_sdwa v229, v209 dst_sel:DWORD dst_unused:UNUSED_PAD src0_sel:WORD_1
	v_cvt_f32_f16_e32 v238, v209
	v_cvt_f32_f16_sdwa v239, v210 dst_sel:DWORD dst_unused:UNUSED_PAD src0_sel:WORD_1
	v_cvt_f32_f16_e32 v240, v210
	v_cvt_f32_f16_sdwa v241, v211 dst_sel:DWORD dst_unused:UNUSED_PAD src0_sel:WORD_1
	v_cvt_f32_f16_e32 v242, v211
	s_waitcnt lgkmcnt(0)
	v_sub_f32_e32 v208, v208, v232
	v_sub_f32_e32 v209, v1, v232
	v_sub_f32_e32 v210, v238, v232
	v_sub_f32_e32 v211, v229, v232
	v_pk_mul_f32 v[210:211], v[232:233], v[210:211] op_sel:[1,0]
	v_pk_mul_f32 v[208:209], v[232:233], v[208:209] op_sel:[1,0]
	v_sub_f32_e32 v238, v240, v232
	v_sub_f32_e32 v239, v239, v232
	v_sub_f32_e32 v240, v242, v232
	v_sub_f32_e32 v241, v241, v232
	v_pk_fma_f32 v[208:209], v[94:95], v[208:209], v[98:99]
	v_pk_fma_f32 v[210:211], v[96:97], v[210:211], v[100:101]
	v_pk_mul_f32 v[240:241], v[232:233], v[240:241] op_sel:[1,0]
	v_pk_mul_f32 v[238:239], v[232:233], v[238:239] op_sel:[1,0]
	v_pk_fma_f32 v[240:241], v[88:89], v[240:241], v[92:93]
	v_pk_fma_f32 v[238:239], v[86:87], v[238:239], v[90:91]
	v_pk_fma_f32 v[168:169], v[210:211], s[18:19], v[168:169] op_sel_hi:[1,0,1]
	v_pk_fma_f32 v[166:167], v[208:209], s[18:19], v[166:167] op_sel_hi:[1,0,1]
	v_pk_fma_f32 v[208:209], v[240:241], s[18:19], v[164:165] op_sel_hi:[1,0,1]
	v_pk_fma_f32 v[164:165], v[238:239], s[18:19], v[162:163] op_sel_hi:[1,0,1]
	v_pk_mov_b32 v[162:163], v[166:167], v[168:169] op_sel:[1,0]
	v_mov_b32_e32 v210, v166
	v_mov_b32_e32 v211, v169
	v_pk_add_f32 v[210:211], v[162:163], v[210:211]
	v_pk_mul_f32 v[162:163], v[168:169], v[168:169]
	v_pk_mul_f32 v[240:241], v[166:167], v[166:167]
	v_lshl_add_u64 v[230:231], v[200:201], 0, v[230:231]
	v_pk_mov_b32 v[242:243], v[240:241], v[162:163] op_sel:[1,0]
	v_mov_b32_e32 v241, v163
	v_pk_add_f32 v[162:163], v[242:243], v[240:241]
	v_add_f32_e32 v238, v164, v165
	v_pk_add_f32 v[240:241], v[162:163], v[162:163] op_sel_hi:[0,1]
	v_mul_f32_e32 v162, v164, v164
	v_pk_fma_f32 v[242:243], v[164:165], v[164:165], v[162:163] op_sel_hi:[1,1,0]
	v_cvt_pk_f16_f32 v162, v166, v167
	v_cvt_pk_f16_f32 v163, v168, v169
	v_cvt_pk_f16_f32 v164, v164, v165
	v_cvt_pk_f16_f32 v165, v208, v209
	global_store_dwordx4 v[230:231], v[162:165], off
	v_cvt_f32_f16_sdwa v167, v214 dst_sel:DWORD dst_unused:UNUSED_PAD src0_sel:WORD_1
	v_cvt_f32_f16_e32 v166, v214
	v_cvt_f32_f16_sdwa v163, v212 dst_sel:DWORD dst_unused:UNUSED_PAD src0_sel:WORD_1
	v_cvt_f32_f16_e32 v162, v212
	v_cvt_f32_f16_sdwa v165, v213 dst_sel:DWORD dst_unused:UNUSED_PAD src0_sel:WORD_1
	v_cvt_f32_f16_e32 v164, v213
	v_cvt_f32_f16_sdwa v169, v215 dst_sel:DWORD dst_unused:UNUSED_PAD src0_sel:WORD_1
	v_cvt_f32_f16_e32 v168, v215
	v_sub_f32_e32 v162, v162, v232
	v_sub_f32_e32 v163, v163, v232
	v_sub_f32_e32 v164, v164, v232
	v_sub_f32_e32 v165, v165, v232
	v_pk_mul_f32 v[164:165], v[232:233], v[164:165] op_sel:[1,0]
	v_pk_mul_f32 v[162:163], v[232:233], v[162:163] op_sel:[1,0]
	v_sub_f32_e32 v166, v166, v232
	v_sub_f32_e32 v167, v167, v232
	v_sub_f32_e32 v168, v168, v232
	v_sub_f32_e32 v169, v169, v232
; #define PG8_LAS __attribute__((address_space(3)))
;     __device__ __forceinline__ void operator()(const f32x4 (&acc)[2][2][4][2], const Unit& u, int ui, int wr, int wc, int fr, int fq) const {
;     ...
;             for (int m = 0; m < 4; ++m) { const int row = row0 + ai * HALF + m * 16; const size_t off = (size_t)row * ldc + col0;
;                 float mu = 0.f, rs = 1.f; if (FOLD) { const f32x2_t ms = ((const PG8_LAS f32x2_t*)tb)[pslot + ai * HALF + wr * 64 + m * 16 + fr]; mu = ms.x; rs = ms.y; }
;                 float ssum = 0.f, ssq = 0.f;
; #pragma unroll
;                 for (int bj = 0; bj < 2; ++bj) { f32x4 v0 = acc[ai][bj][m][0], v1 = acc[ai][bj][m][1];
;                     if (FOLD && MODE != 2) { v0 = (v0 - mu * cv[bj][0]) * rs + bv[bj][0]; v1 = (v1 - mu * cv[bj][1]) * rs + bv[bj][1]; }
;                     if (MODE == 0) { v0 = v0 * sc; v1 = v1 * sc; }
;                     if (MODE == 1) { v0 = __builtin_elementwise_max(v0, (f32x4){0.f, 0.f, 0.f, 0.f}); v1 = __builtin_elementwise_max(v1, (f32x4){0.f, 0.f, 0.f, 0.f}); v0 = v0 * v0; v1 = v1 * v1; }
;                     if (MODE == 2) { const bf16x8 r = rr[m][bj];
;                         f32x4 h0 = (f32x4){(float)r[0], (float)r[1], (float)r[2], (float)r[3]}, h1 = (f32x4){(float)r[4], (float)r[5], (float)r[6], (float)r[7]};
;                         if (FOLD) { h0 = (h0 - mu) * rs * cv[bj][0] + bv[bj][0]; h1 = (h1 - mu) * rs * cv[bj][1] + bv[bj][1]; }
;                         v0 = v0 + alpha * h0; v1 = v1 + alpha * h1;
;                         ssum += (v0[0] + v0[1]) + (v0[2] + v0[3]) + (v1[0] + v1[1]) + (v1[2] + v1[3]);
;                         ssq += (v0[0] * v0[0] + v0[1] * v0[1]) + (v0[2] * v0[2] + v0[3] * v0[3]) + (v1[0] * v1[0] + v1[1] * v1[1]) + (v1[2] * v1[2] + v1[3] * v1[3]); }
;                     u32x4 w; w.x = pk2h(v0[0], v0[1]); w.y = pk2h(v0[2], v0[3]); w.z = pk2h(v1[0], v1[1]); w.w = pk2h(v1[2], v1[3]);
;                     if (MODE == 0 && hm) { const int cc = col0 + bj * HALF; *(u32x4*)(base + ((size_t)(row >> 11) * 16 + (cc >> 6)) * 131072 + (size_t)(row & 2047) * 64 + (cc & 63)) = w; }
;                     else *(u32x4*)(base + off + bj * HALF) = w; }
;                 if (MODE == 2) { ssum += __shfl_xor(ssum, 16); ssq += __shfl_xor(ssq, 16); ssum += __shfl_xor(ssum, 32); ssq += __shfl_xor(ssq, 32);
	v_pk_fma_f32 v[162:163], v[78:79], v[162:163], v[82:83]
	v_pk_fma_f32 v[164:165], v[80:81], v[164:165], v[84:85]
	v_pk_mul_f32 v[168:169], v[232:233], v[168:169] op_sel:[1,0]
	v_pk_mul_f32 v[166:167], v[232:233], v[166:167] op_sel:[1,0]
	v_pk_fma_f32 v[168:169], v[68:69], v[168:169], v[72:73]
	v_pk_fma_f32 v[166:167], v[66:67], v[166:167], v[70:71]
	v_pk_fma_f32 v[156:157], v[164:165], s[18:19], v[156:157] op_sel_hi:[1,0,1]
	v_pk_fma_f32 v[154:155], v[162:163], s[18:19], v[154:155] op_sel_hi:[1,0,1]
	v_pk_fma_f32 v[162:163], v[168:169], s[18:19], v[152:153] op_sel_hi:[1,0,1]
	v_pk_fma_f32 v[152:153], v[166:167], s[18:19], v[150:151] op_sel_hi:[1,0,1]
	v_pk_mov_b32 v[150:151], v[154:155], v[156:157] op_sel:[1,0]
	v_mov_b32_e32 v164, v154
	v_mov_b32_e32 v165, v157
	v_pk_add_f32 v[164:165], v[150:151], v[164:165]
	v_mul_f32_e32 v150, v154, v154
	v_pk_fma_f32 v[166:167], v[154:155], v[154:155], v[150:151] op_sel_hi:[1,1,0]
	v_mul_f32_e32 v150, v156, v156
	v_pk_fma_f32 v[168:169], v[156:157], v[156:157], v[150:151] op_sel_hi:[1,1,0]
	v_mul_f32_e32 v150, v162, v162
	v_add_f32_e32 v244, v152, v153
	v_mul_f32_e32 v239, v152, v152
	v_mul_f32_e32 v214, v153, v153
	v_pk_fma_f32 v[212:213], v[162:163], v[162:163], v[150:151] op_sel_hi:[1,1,0]
	v_cvt_pk_f16_f32 v150, v154, v155
	v_cvt_pk_f16_f32 v151, v156, v157
	v_cvt_pk_f16_f32 v152, v152, v153
	v_cvt_pk_f16_f32 v153, v162, v163
	v_mul_f32_e32 v1, v209, v209
	global_store_dwordx4 v[230:231], v[150:153], off offset:256
	v_mul_f32_e32 v245, v208, v208
	v_mov_b32_e32 v242, v162
	v_pk_add_f32 v[150:151], v[164:165], v[164:165] op_sel:[0,1] op_sel_hi:[1,0]
	v_mov_b32_e32 v240, v163
	v_mov_b32_e32 v151, v1
	v_pk_add_f32 v[154:155], v[210:211], v[210:211] op_sel:[0,1] op_sel_hi:[1,0]
	v_pk_add_f32 v[150:151], v[244:245], v[150:151]
	v_pk_add_f32 v[152:153], v[242:243], v[240:241]
	v_mov_b32_e32 v166, v208
	v_mov_b32_e32 v168, v209
	v_mov_b32_e32 v155, v214
	v_pk_add_f32 v[150:151], v[150:151], v[152:153]
	v_pk_add_f32 v[152:153], v[166:167], v[168:169]
	v_pk_add_f32 v[154:155], v[238:239], v[154:155]
	v_mov_b32_e32 v1, v213
	v_pk_add_f32 v[152:153], v[154:155], v[152:153]
	s_nop 0
	v_pk_add_f32 v[152:153], v[152:153], v[0:1]
	s_nop 0
	v_pk_add_f32 v[150:151], v[150:151], v[152:153]
	ds_bpermute_b32 v152, v227, v150
	ds_bpermute_b32 v153, v227, v151
	s_waitcnt lgkmcnt(0)
	v_pk_add_f32 v[150:151], v[150:151], v[152:153]
	ds_bpermute_b32 v152, v226, v150
	ds_bpermute_b32 v153, v226, v151
	s_and_saveexec_b64 s[22:23], s[36:37]
	s_cbranch_execz .LBB0_1139
	s_waitcnt lgkmcnt(0)
	v_pk_add_f32 v[150:151], v[150:151], v[152:153]
	v_lshlrev_b64 v[152:153], 7, v[202:203]
	v_lshl_add_u64 v[152:153], s[44:45], 0, v[152:153]
	v_lshl_add_u64 v[152:153], vcc, 3, v[152:153]
	s_lshl_b32 s58, s71, 3
	v_lshl_add_u64 v[152:153], v[152:153], 0, s[58:59]
	global_store_dwordx2 v[152:153], v[150:151], off
.LBB0_1139:
	s_or_b64 exec, exec, s[22:23]
	s_waitcnt vmcnt(6)
	s_waitcnt lgkmcnt(0)
	ds_read_b64 v[152:153], v228 offset:128
	v_cvt_f32_f16_sdwa v1, v186 dst_sel:DWORD dst_unused:UNUSED_PAD src0_sel:WORD_1
	v_cvt_f32_f16_e32 v154, v186
	v_cvt_f32_f16_sdwa v156, v187 dst_sel:DWORD dst_unused:UNUSED_PAD src0_sel:WORD_1
	v_cvt_f32_f16_e32 v162, v187
	v_cvt_f32_f16_sdwa v163, v188 dst_sel:DWORD dst_unused:UNUSED_PAD src0_sel:WORD_1
	v_cvt_f32_f16_e32 v164, v188
	v_cvt_f32_f16_sdwa v165, v189 dst_sel:DWORD dst_unused:UNUSED_PAD src0_sel:WORD_1
	v_cvt_f32_f16_e32 v166, v189
	s_waitcnt lgkmcnt(0)
	v_sub_f32_e32 v155, v1, v152
	v_sub_f32_e32 v157, v156, v152
	v_sub_f32_e32 v154, v154, v152
	v_sub_f32_e32 v156, v162, v152
	v_pk_mul_f32 v[156:157], v[152:153], v[156:157] op_sel:[1,0]
	v_pk_mul_f32 v[154:155], v[152:153], v[154:155] op_sel:[1,0]
	v_sub_f32_e32 v163, v163, v152
	v_sub_f32_e32 v165, v165, v152
	v_sub_f32_e32 v162, v164, v152
	v_sub_f32_e32 v164, v166, v152
	v_pk_fma_f32 v[154:155], v[94:95], v[154:155], v[98:99]
	v_pk_fma_f32 v[156:157], v[96:97], v[156:157], v[100:101]
	v_pk_mul_f32 v[164:165], v[152:153], v[164:165] op_sel:[1,0]
	v_pk_mul_f32 v[162:163], v[152:153], v[162:163] op_sel:[1,0]
	v_pk_fma_f32 v[164:165], v[88:89], v[164:165], v[92:93]
	v_pk_fma_f32 v[162:163], v[86:87], v[162:163], v[90:91]
	v_pk_fma_f32 v[148:149], v[156:157], s[18:19], v[148:149] op_sel_hi:[1,0,1]
	v_pk_fma_f32 v[146:147], v[154:155], s[18:19], v[146:147] op_sel_hi:[1,0,1]
	v_pk_fma_f32 v[154:155], v[164:165], s[18:19], v[144:145] op_sel_hi:[1,0,1]
	v_pk_fma_f32 v[144:145], v[162:163], s[18:19], v[142:143] op_sel_hi:[1,0,1]
	v_pk_mov_b32 v[142:143], v[146:147], v[148:149] op_sel:[1,0]
	v_mov_b32_e32 v156, v146
	v_mov_b32_e32 v157, v149
	v_pk_add_f32 v[156:157], v[142:143], v[156:157]
	v_pk_mul_f32 v[142:143], v[148:149], v[148:149]
	v_pk_mul_f32 v[164:165], v[146:147], v[146:147]
	v_lshlrev_b64 v[150:151], 10, v[220:221]
	v_pk_mov_b32 v[166:167], v[164:165], v[142:143] op_sel:[1,0]
	v_mov_b32_e32 v165, v143
	v_pk_add_f32 v[142:143], v[166:167], v[164:165]
	v_lshl_add_u64 v[150:151], v[150:151], 1, v[200:201]
	v_pk_add_f32 v[164:165], v[142:143], v[142:143] op_sel_hi:[0,1]
	v_mul_f32_e32 v142, v144, v144
	v_add_f32_e32 v162, v144, v145
	v_pk_fma_f32 v[166:167], v[144:145], v[144:145], v[142:143] op_sel_hi:[1,1,0]
	v_cvt_pk_f16_f32 v142, v146, v147
	v_cvt_pk_f16_f32 v143, v148, v149
	v_cvt_pk_f16_f32 v144, v144, v145
	v_cvt_pk_f16_f32 v145, v154, v155
	global_store_dwordx4 v[150:151], v[142:145], off
	v_cvt_f32_f16_e32 v146, v183
	v_cvt_f32_f16_sdwa v147, v184 dst_sel:DWORD dst_unused:UNUSED_PAD src0_sel:WORD_1
	v_cvt_f32_f16_sdwa v142, v182 dst_sel:DWORD dst_unused:UNUSED_PAD src0_sel:WORD_1
	v_cvt_f32_f16_e32 v144, v182
; #define PG8_LAS __attribute__((address_space(3)))
;     __device__ __forceinline__ void operator()(const f32x4 (&acc)[2][2][4][2], const Unit& u, int ui, int wr, int wc, int fr, int fq) const {
;     ...
;             for (int m = 0; m < 4; ++m) { const int row = row0 + ai * HALF + m * 16; const size_t off = (size_t)row * ldc + col0;
;                 float mu = 0.f, rs = 1.f; if (FOLD) { const f32x2_t ms = ((const PG8_LAS f32x2_t*)tb)[pslot + ai * HALF + wr * 64 + m * 16 + fr]; mu = ms.x; rs = ms.y; }
;                 float ssum = 0.f, ssq = 0.f;
; #pragma unroll
;                 for (int bj = 0; bj < 2; ++bj) { f32x4 v0 = acc[ai][bj][m][0], v1 = acc[ai][bj][m][1];
;                     if (FOLD && MODE != 2) { v0 = (v0 - mu * cv[bj][0]) * rs + bv[bj][0]; v1 = (v1 - mu * cv[bj][1]) * rs + bv[bj][1]; }
;                     if (MODE == 0) { v0 = v0 * sc; v1 = v1 * sc; }
;                     if (MODE == 1) { v0 = __builtin_elementwise_max(v0, (f32x4){0.f, 0.f, 0.f, 0.f}); v1 = __builtin_elementwise_max(v1, (f32x4){0.f, 0.f, 0.f, 0.f}); v0 = v0 * v0; v1 = v1 * v1; }
;                     if (MODE == 2) { const bf16x8 r = rr[m][bj];
;                         f32x4 h0 = (f32x4){(float)r[0], (float)r[1], (float)r[2], (float)r[3]}, h1 = (f32x4){(float)r[4], (float)r[5], (float)r[6], (float)r[7]};
;                         if (FOLD) { h0 = (h0 - mu) * rs * cv[bj][0] + bv[bj][0]; h1 = (h1 - mu) * rs * cv[bj][1] + bv[bj][1]; }
;                         v0 = v0 + alpha * h0; v1 = v1 + alpha * h1;
;                         ssum += (v0[0] + v0[1]) + (v0[2] + v0[3]) + (v1[0] + v1[1]) + (v1[2] + v1[3]);
;                         ssq += (v0[0] * v0[0] + v0[1] * v0[1]) + (v0[2] * v0[2] + v0[3] * v0[3]) + (v1[0] * v1[0] + v1[1] * v1[1]) + (v1[2] * v1[2] + v1[3] * v1[3]); }
;                     u32x4 w; w.x = pk2h(v0[0], v0[1]); w.y = pk2h(v0[2], v0[3]); w.z = pk2h(v1[0], v1[1]); w.w = pk2h(v1[2], v1[3]);
;                     if (MODE == 0 && hm) { const int cc = col0 + bj * HALF; *(u32x4*)(base + ((size_t)(row >> 11) * 16 + (cc >> 6)) * 131072 + (size_t)(row & 2047) * 64 + (cc & 63)) = w; }
;                     else *(u32x4*)(base + off + bj * HALF) = w; }
;                 if (MODE == 2) { ssum += __shfl_xor(ssum, 16); ssq += __shfl_xor(ssq, 16); ssum += __shfl_xor(ssum, 32); ssq += __shfl_xor(ssq, 32);
	v_cvt_f32_f16_sdwa v145, v183 dst_sel:DWORD dst_unused:UNUSED_PAD src0_sel:WORD_1
	v_cvt_f32_f16_e32 v148, v184
	v_cvt_f32_f16_sdwa v149, v185 dst_sel:DWORD dst_unused:UNUSED_PAD src0_sel:WORD_1
	v_cvt_f32_f16_e32 v163, v185
	v_sub_f32_e32 v143, v142, v152
	v_sub_f32_e32 v145, v145, v152
	v_sub_f32_e32 v142, v144, v152
	v_sub_f32_e32 v144, v146, v152
	v_pk_mul_f32 v[144:145], v[152:153], v[144:145] op_sel:[1,0]
	v_pk_mul_f32 v[142:143], v[152:153], v[142:143] op_sel:[1,0]
	v_sub_f32_e32 v147, v147, v152
	v_sub_f32_e32 v149, v149, v152
	v_sub_f32_e32 v146, v148, v152
	v_sub_f32_e32 v148, v163, v152
	v_pk_fma_f32 v[142:143], v[78:79], v[142:143], v[82:83]
	v_pk_fma_f32 v[144:145], v[80:81], v[144:145], v[84:85]
	v_pk_mul_f32 v[148:149], v[152:153], v[148:149] op_sel:[1,0]
	v_pk_mul_f32 v[146:147], v[152:153], v[146:147] op_sel:[1,0]
	v_pk_fma_f32 v[148:149], v[68:69], v[148:149], v[72:73]
	v_pk_fma_f32 v[146:147], v[66:67], v[146:147], v[70:71]
	v_pk_fma_f32 v[140:141], v[144:145], s[18:19], v[140:141] op_sel_hi:[1,0,1]
	v_pk_fma_f32 v[138:139], v[142:143], s[18:19], v[138:139] op_sel_hi:[1,0,1]
	v_pk_fma_f32 v[142:143], v[148:149], s[18:19], v[136:137] op_sel_hi:[1,0,1]
	v_pk_fma_f32 v[136:137], v[146:147], s[18:19], v[134:135] op_sel_hi:[1,0,1]
	v_pk_mov_b32 v[134:135], v[138:139], v[140:141] op_sel:[1,0]
	v_mov_b32_e32 v144, v138
	v_mov_b32_e32 v145, v141
	v_pk_add_f32 v[144:145], v[134:135], v[144:145]
	v_mul_f32_e32 v134, v138, v138
	v_pk_fma_f32 v[146:147], v[138:139], v[138:139], v[134:135] op_sel_hi:[1,1,0]
	v_mul_f32_e32 v134, v140, v140
	v_pk_fma_f32 v[148:149], v[140:141], v[140:141], v[134:135] op_sel_hi:[1,1,0]
	v_mul_f32_e32 v134, v142, v142
	v_add_f32_e32 v168, v136, v137
	v_mul_f32_e32 v163, v136, v136
	v_mul_f32_e32 v182, v137, v137
	v_pk_fma_f32 v[152:153], v[142:143], v[142:143], v[134:135] op_sel_hi:[1,1,0]
	v_cvt_pk_f16_f32 v134, v138, v139
	v_cvt_pk_f16_f32 v135, v140, v141
	v_cvt_pk_f16_f32 v136, v136, v137
	v_cvt_pk_f16_f32 v137, v142, v143
	v_mul_f32_e32 v1, v155, v155
	global_store_dwordx4 v[150:151], v[134:137], off offset:256
	v_mul_f32_e32 v169, v154, v154
	v_mov_b32_e32 v166, v142
	v_pk_add_f32 v[134:135], v[144:145], v[144:145] op_sel:[0,1] op_sel_hi:[1,0]
	v_mov_b32_e32 v164, v143
	v_mov_b32_e32 v135, v1
	v_pk_add_f32 v[138:139], v[156:157], v[156:157] op_sel:[0,1] op_sel_hi:[1,0]
	v_pk_add_f32 v[134:135], v[168:169], v[134:135]
	v_pk_add_f32 v[136:137], v[166:167], v[164:165]
	v_mov_b32_e32 v146, v154
	v_mov_b32_e32 v148, v155
	v_mov_b32_e32 v139, v182
	v_pk_add_f32 v[134:135], v[134:135], v[136:137]
	v_pk_add_f32 v[136:137], v[146:147], v[148:149]
	v_pk_add_f32 v[138:139], v[162:163], v[138:139]
	v_mov_b32_e32 v1, v153
	v_pk_add_f32 v[136:137], v[138:139], v[136:137]
	s_nop 0
	v_pk_add_f32 v[136:137], v[136:137], v[0:1]
	s_nop 0
	v_pk_add_f32 v[134:135], v[134:135], v[136:137]
	ds_bpermute_b32 v136, v227, v134
	ds_bpermute_b32 v137, v227, v135
	s_waitcnt lgkmcnt(0)
	v_pk_add_f32 v[134:135], v[134:135], v[136:137]
	ds_bpermute_b32 v136, v226, v134
	ds_bpermute_b32 v137, v226, v135
	s_and_saveexec_b64 s[22:23], s[36:37]
	s_cbranch_execz .LBB0_1141
	s_waitcnt lgkmcnt(0)
	v_pk_add_f32 v[134:135], v[134:135], v[136:137]
	v_lshlrev_b64 v[136:137], 7, v[220:221]
	v_lshl_add_u64 v[136:137], s[44:45], 0, v[136:137]
	v_lshl_add_u64 v[136:137], vcc, 3, v[136:137]
	s_lshl_b32 s58, s71, 3
	v_lshl_add_u64 v[136:137], v[136:137], 0, s[58:59]
	global_store_dwordx2 v[136:137], v[134:135], off
.LBB0_1141:
	s_or_b64 exec, exec, s[22:23]
	s_waitcnt vmcnt(6)
	s_waitcnt lgkmcnt(0)
	ds_read_b64 v[136:137], v228 offset:256
	v_cvt_f32_f16_sdwa v1, v178 dst_sel:DWORD dst_unused:UNUSED_PAD src0_sel:WORD_1
	v_cvt_f32_f16_e32 v138, v178
	v_cvt_f32_f16_sdwa v140, v179 dst_sel:DWORD dst_unused:UNUSED_PAD src0_sel:WORD_1
	v_cvt_f32_f16_e32 v142, v179
	v_cvt_f32_f16_sdwa v143, v180 dst_sel:DWORD dst_unused:UNUSED_PAD src0_sel:WORD_1
	v_cvt_f32_f16_e32 v144, v180
	v_cvt_f32_f16_sdwa v145, v181 dst_sel:DWORD dst_unused:UNUSED_PAD src0_sel:WORD_1
	v_cvt_f32_f16_e32 v146, v181
	s_waitcnt lgkmcnt(0)
	v_sub_f32_e32 v139, v1, v136
	v_sub_f32_e32 v141, v140, v136
	v_sub_f32_e32 v138, v138, v136
	v_sub_f32_e32 v140, v142, v136
	v_pk_mul_f32 v[140:141], v[136:137], v[140:141] op_sel:[1,0]
	v_pk_mul_f32 v[138:139], v[136:137], v[138:139] op_sel:[1,0]
	v_sub_f32_e32 v143, v143, v136
	v_sub_f32_e32 v145, v145, v136
	v_sub_f32_e32 v142, v144, v136
	v_sub_f32_e32 v144, v146, v136
	v_pk_fma_f32 v[138:139], v[94:95], v[138:139], v[98:99]
	v_pk_fma_f32 v[140:141], v[96:97], v[140:141], v[100:101]
	v_pk_mul_f32 v[144:145], v[136:137], v[144:145] op_sel:[1,0]
	v_pk_mul_f32 v[142:143], v[136:137], v[142:143] op_sel:[1,0]
	v_pk_fma_f32 v[144:145], v[88:89], v[144:145], v[92:93]
	v_pk_fma_f32 v[142:143], v[86:87], v[142:143], v[90:91]
	v_pk_fma_f32 v[132:133], v[140:141], s[18:19], v[132:133] op_sel_hi:[1,0,1]
	v_pk_fma_f32 v[130:131], v[138:139], s[18:19], v[130:131] op_sel_hi:[1,0,1]
	v_pk_fma_f32 v[138:139], v[144:145], s[18:19], v[128:129] op_sel_hi:[1,0,1]
	v_pk_fma_f32 v[128:129], v[142:143], s[18:19], v[126:127] op_sel_hi:[1,0,1]
	v_pk_mov_b32 v[126:127], v[130:131], v[132:133] op_sel:[1,0]
	v_mov_b32_e32 v140, v130
	v_mov_b32_e32 v141, v133
	v_pk_add_f32 v[140:141], v[126:127], v[140:141]
	v_pk_mul_f32 v[126:127], v[132:133], v[132:133]
	v_pk_mul_f32 v[144:145], v[130:131], v[130:131]
	v_lshlrev_b64 v[134:135], 10, v[218:219]
	v_pk_mov_b32 v[146:147], v[144:145], v[126:127] op_sel:[1,0]
	v_mov_b32_e32 v145, v127
	v_pk_add_f32 v[126:127], v[146:147], v[144:145]
	v_lshl_add_u64 v[134:135], v[134:135], 1, v[200:201]
	v_pk_add_f32 v[144:145], v[126:127], v[126:127] op_sel_hi:[0,1]
; #define PG8_LAS __attribute__((address_space(3)))
;     __device__ __forceinline__ void operator()(const f32x4 (&acc)[2][2][4][2], const Unit& u, int ui, int wr, int wc, int fr, int fq) const {
;     ...
;             for (int m = 0; m < 4; ++m) { const int row = row0 + ai * HALF + m * 16; const size_t off = (size_t)row * ldc + col0;
;                 float mu = 0.f, rs = 1.f; if (FOLD) { const f32x2_t ms = ((const PG8_LAS f32x2_t*)tb)[pslot + ai * HALF + wr * 64 + m * 16 + fr]; mu = ms.x; rs = ms.y; }
;                 float ssum = 0.f, ssq = 0.f;
; #pragma unroll
;                 for (int bj = 0; bj < 2; ++bj) { f32x4 v0 = acc[ai][bj][m][0], v1 = acc[ai][bj][m][1];
;                     if (FOLD && MODE != 2) { v0 = (v0 - mu * cv[bj][0]) * rs + bv[bj][0]; v1 = (v1 - mu * cv[bj][1]) * rs + bv[bj][1]; }
;                     if (MODE == 0) { v0 = v0 * sc; v1 = v1 * sc; }
;                     if (MODE == 1) { v0 = __builtin_elementwise_max(v0, (f32x4){0.f, 0.f, 0.f, 0.f}); v1 = __builtin_elementwise_max(v1, (f32x4){0.f, 0.f, 0.f, 0.f}); v0 = v0 * v0; v1 = v1 * v1; }
;                     if (MODE == 2) { const bf16x8 r = rr[m][bj];
;                         f32x4 h0 = (f32x4){(float)r[0], (float)r[1], (float)r[2], (float)r[3]}, h1 = (f32x4){(float)r[4], (float)r[5], (float)r[6], (float)r[7]};
;                         if (FOLD) { h0 = (h0 - mu) * rs * cv[bj][0] + bv[bj][0]; h1 = (h1 - mu) * rs * cv[bj][1] + bv[bj][1]; }
;                         v0 = v0 + alpha * h0; v1 = v1 + alpha * h1;
;                         ssum += (v0[0] + v0[1]) + (v0[2] + v0[3]) + (v1[0] + v1[1]) + (v1[2] + v1[3]);
;                         ssq += (v0[0] * v0[0] + v0[1] * v0[1]) + (v0[2] * v0[2] + v0[3] * v0[3]) + (v1[0] * v1[0] + v1[1] * v1[1]) + (v1[2] * v1[2] + v1[3] * v1[3]); }
;                     u32x4 w; w.x = pk2h(v0[0], v0[1]); w.y = pk2h(v0[2], v0[3]); w.z = pk2h(v1[0], v1[1]); w.w = pk2h(v1[2], v1[3]);
;                     if (MODE == 0 && hm) { const int cc = col0 + bj * HALF; *(u32x4*)(base + ((size_t)(row >> 11) * 16 + (cc >> 6)) * 131072 + (size_t)(row & 2047) * 64 + (cc & 63)) = w; }
;                     else *(u32x4*)(base + off + bj * HALF) = w; }
;                 if (MODE == 2) { ssum += __shfl_xor(ssum, 16); ssq += __shfl_xor(ssq, 16); ssum += __shfl_xor(ssum, 32); ssq += __shfl_xor(ssq, 32);
	v_mul_f32_e32 v126, v128, v128
	v_add_f32_e32 v142, v128, v129
	v_pk_fma_f32 v[146:147], v[128:129], v[128:129], v[126:127] op_sel_hi:[1,1,0]
	v_cvt_pk_f16_f32 v126, v130, v131
	v_cvt_pk_f16_f32 v127, v132, v133
	v_cvt_pk_f16_f32 v128, v128, v129
	v_cvt_pk_f16_f32 v129, v138, v139
	global_store_dwordx4 v[134:135], v[126:129], off
	v_cvt_f32_f16_e32 v130, v175
	v_cvt_f32_f16_sdwa v131, v176 dst_sel:DWORD dst_unused:UNUSED_PAD src0_sel:WORD_1
	v_cvt_f32_f16_sdwa v126, v174 dst_sel:DWORD dst_unused:UNUSED_PAD src0_sel:WORD_1
	v_cvt_f32_f16_e32 v128, v174
	v_cvt_f32_f16_sdwa v129, v175 dst_sel:DWORD dst_unused:UNUSED_PAD src0_sel:WORD_1
	v_cvt_f32_f16_e32 v132, v176
	v_cvt_f32_f16_sdwa v133, v177 dst_sel:DWORD dst_unused:UNUSED_PAD src0_sel:WORD_1
	v_cvt_f32_f16_e32 v143, v177
	v_sub_f32_e32 v127, v126, v136
	v_sub_f32_e32 v129, v129, v136
	v_sub_f32_e32 v126, v128, v136
	v_sub_f32_e32 v128, v130, v136
	v_pk_mul_f32 v[128:129], v[136:137], v[128:129] op_sel:[1,0]
	v_pk_mul_f32 v[126:127], v[136:137], v[126:127] op_sel:[1,0]
	v_sub_f32_e32 v131, v131, v136
	v_sub_f32_e32 v133, v133, v136
	v_sub_f32_e32 v130, v132, v136
	v_sub_f32_e32 v132, v143, v136
	v_pk_fma_f32 v[126:127], v[78:79], v[126:127], v[82:83]
	v_pk_fma_f32 v[128:129], v[80:81], v[128:129], v[84:85]
	v_pk_mul_f32 v[132:133], v[136:137], v[132:133] op_sel:[1,0]
	v_pk_mul_f32 v[130:131], v[136:137], v[130:131] op_sel:[1,0]
	v_pk_fma_f32 v[132:133], v[68:69], v[132:133], v[72:73]
	v_pk_fma_f32 v[130:131], v[66:67], v[130:131], v[70:71]
	v_pk_fma_f32 v[124:125], v[128:129], s[18:19], v[124:125] op_sel_hi:[1,0,1]
	v_pk_fma_f32 v[122:123], v[126:127], s[18:19], v[122:123] op_sel_hi:[1,0,1]
	v_pk_fma_f32 v[126:127], v[132:133], s[18:19], v[120:121] op_sel_hi:[1,0,1]
	v_pk_fma_f32 v[120:121], v[130:131], s[18:19], v[118:119] op_sel_hi:[1,0,1]
	v_pk_mov_b32 v[118:119], v[122:123], v[124:125] op_sel:[1,0]
	v_mov_b32_e32 v128, v122
	v_mov_b32_e32 v129, v125
	v_pk_add_f32 v[128:129], v[118:119], v[128:129]
	v_mul_f32_e32 v118, v122, v122
	v_pk_fma_f32 v[130:131], v[122:123], v[122:123], v[118:119] op_sel_hi:[1,1,0]
	v_mul_f32_e32 v118, v124, v124
	v_pk_fma_f32 v[132:133], v[124:125], v[124:125], v[118:119] op_sel_hi:[1,1,0]
	v_mul_f32_e32 v118, v126, v126
	v_add_f32_e32 v148, v120, v121
	v_mul_f32_e32 v143, v120, v120
	v_mul_f32_e32 v150, v121, v121
	v_pk_fma_f32 v[136:137], v[126:127], v[126:127], v[118:119] op_sel_hi:[1,1,0]
	v_cvt_pk_f16_f32 v118, v122, v123
	v_cvt_pk_f16_f32 v119, v124, v125
	v_cvt_pk_f16_f32 v120, v120, v121
	v_cvt_pk_f16_f32 v121, v126, v127
	v_mul_f32_e32 v1, v139, v139
	global_store_dwordx4 v[134:135], v[118:121], off offset:256
	v_mul_f32_e32 v149, v138, v138
	v_mov_b32_e32 v146, v126
	v_pk_add_f32 v[118:119], v[128:129], v[128:129] op_sel:[0,1] op_sel_hi:[1,0]
	v_mov_b32_e32 v144, v127
	v_mov_b32_e32 v119, v1
	v_pk_add_f32 v[122:123], v[140:141], v[140:141] op_sel:[0,1] op_sel_hi:[1,0]
	v_pk_add_f32 v[118:119], v[148:149], v[118:119]
	v_pk_add_f32 v[120:121], v[146:147], v[144:145]
	v_mov_b32_e32 v130, v138
	v_mov_b32_e32 v132, v139
	v_mov_b32_e32 v123, v150
	v_pk_add_f32 v[118:119], v[118:119], v[120:121]
	v_pk_add_f32 v[120:121], v[130:131], v[132:133]
	v_pk_add_f32 v[122:123], v[142:143], v[122:123]
	v_mov_b32_e32 v1, v137
	v_pk_add_f32 v[120:121], v[122:123], v[120:121]
	s_nop 0
	v_pk_add_f32 v[120:121], v[120:121], v[0:1]
	s_nop 0
	v_pk_add_f32 v[118:119], v[118:119], v[120:121]
	ds_bpermute_b32 v120, v227, v118
	ds_bpermute_b32 v121, v227, v119
	s_waitcnt lgkmcnt(0)
	v_pk_add_f32 v[118:119], v[118:119], v[120:121]
	ds_bpermute_b32 v120, v226, v118
	ds_bpermute_b32 v121, v226, v119
	s_and_saveexec_b64 s[22:23], s[36:37]
	v_readlane_b32 s54, v255, 25
	v_readlane_b32 s55, v255, 26
	s_cbranch_execz .LBB0_1143
	s_waitcnt lgkmcnt(0)
	v_pk_add_f32 v[118:119], v[118:119], v[120:121]
	v_lshlrev_b64 v[120:121], 7, v[218:219]
	v_lshl_add_u64 v[120:121], s[44:45], 0, v[120:121]
	v_lshl_add_u64 v[120:121], vcc, 3, v[120:121]
	s_lshl_b32 s58, s71, 3
	v_lshl_add_u64 v[120:121], v[120:121], 0, s[58:59]
	global_store_dwordx2 v[120:121], v[118:119], off
; #define PG8_LAS __attribute__((address_space(3)))
;     __device__ __forceinline__ void operator()(const f32x4 (&acc)[2][2][4][2], const Unit& u, int ui, int wr, int wc, int fr, int fq) const {
;     ...
;             for (int m = 0; m < 4; ++m) { const int row = row0 + ai * HALF + m * 16; const size_t off = (size_t)row * ldc + col0;
;                 float mu = 0.f, rs = 1.f; if (FOLD) { const f32x2_t ms = ((const PG8_LAS f32x2_t*)tb)[pslot + ai * HALF + wr * 64 + m * 16 + fr]; mu = ms.x; rs = ms.y; }
;                 float ssum = 0.f, ssq = 0.f;
; #pragma unroll
;                 for (int bj = 0; bj < 2; ++bj) { f32x4 v0 = acc[ai][bj][m][0], v1 = acc[ai][bj][m][1];
;                     if (FOLD && MODE != 2) { v0 = (v0 - mu * cv[bj][0]) * rs + bv[bj][0]; v1 = (v1 - mu * cv[bj][1]) * rs + bv[bj][1]; }
;                     if (MODE == 0) { v0 = v0 * sc; v1 = v1 * sc; }
;                     if (MODE == 1) { v0 = __builtin_elementwise_max(v0, (f32x4){0.f, 0.f, 0.f, 0.f}); v1 = __builtin_elementwise_max(v1, (f32x4){0.f, 0.f, 0.f, 0.f}); v0 = v0 * v0; v1 = v1 * v1; }
;                     if (MODE == 2) { const bf16x8 r = rr[m][bj];
;                         f32x4 h0 = (f32x4){(float)r[0], (float)r[1], (float)r[2], (float)r[3]}, h1 = (f32x4){(float)r[4], (float)r[5], (float)r[6], (float)r[7]};
;                         if (FOLD) { h0 = (h0 - mu) * rs * cv[bj][0] + bv[bj][0]; h1 = (h1 - mu) * rs * cv[bj][1] + bv[bj][1]; }
;                         v0 = v0 + alpha * h0; v1 = v1 + alpha * h1;
;                         ssum += (v0[0] + v0[1]) + (v0[2] + v0[3]) + (v1[0] + v1[1]) + (v1[2] + v1[3]);
;                         ssq += (v0[0] * v0[0] + v0[1] * v0[1]) + (v0[2] * v0[2] + v0[3] * v0[3]) + (v1[0] * v1[0] + v1[1] * v1[1]) + (v1[2] * v1[2] + v1[3] * v1[3]); }
;                     u32x4 w; w.x = pk2h(v0[0], v0[1]); w.y = pk2h(v0[2], v0[3]); w.z = pk2h(v1[0], v1[1]); w.w = pk2h(v1[2], v1[3]);
;                     if (MODE == 0 && hm) { const int cc = col0 + bj * HALF; *(u32x4*)(base + ((size_t)(row >> 11) * 16 + (cc >> 6)) * 131072 + (size_t)(row & 2047) * 64 + (cc & 63)) = w; }
;                     else *(u32x4*)(base + off + bj * HALF) = w; }
;                 if (MODE == 2) { ssum += __shfl_xor(ssum, 16); ssq += __shfl_xor(ssq, 16); ssum += __shfl_xor(ssum, 32); ssq += __shfl_xor(ssq, 32);
.LBB0_1143:
	s_or_b64 exec, exec, s[22:23]
	s_waitcnt vmcnt(6)
	s_waitcnt lgkmcnt(0)
	ds_read_b64 v[120:121], v228 offset:384
	v_cvt_f32_f16_sdwa v1, v170 dst_sel:DWORD dst_unused:UNUSED_PAD src0_sel:WORD_1
	v_cvt_f32_f16_e32 v122, v170
	v_cvt_f32_f16_sdwa v124, v171 dst_sel:DWORD dst_unused:UNUSED_PAD src0_sel:WORD_1
	v_cvt_f32_f16_e32 v126, v171
	v_cvt_f32_f16_sdwa v127, v172 dst_sel:DWORD dst_unused:UNUSED_PAD src0_sel:WORD_1
	v_cvt_f32_f16_e32 v128, v172
	v_cvt_f32_f16_sdwa v129, v173 dst_sel:DWORD dst_unused:UNUSED_PAD src0_sel:WORD_1
	v_cvt_f32_f16_e32 v130, v173
	s_waitcnt lgkmcnt(0)
	v_sub_f32_e32 v123, v1, v120
	v_sub_f32_e32 v125, v124, v120
	v_sub_f32_e32 v122, v122, v120
	v_sub_f32_e32 v124, v126, v120
	v_pk_mul_f32 v[124:125], v[120:121], v[124:125] op_sel:[1,0]
	v_pk_mul_f32 v[122:123], v[120:121], v[122:123] op_sel:[1,0]
	v_sub_f32_e32 v127, v127, v120
	v_sub_f32_e32 v129, v129, v120
	v_sub_f32_e32 v126, v128, v120
	v_sub_f32_e32 v128, v130, v120
	v_pk_fma_f32 v[122:123], v[94:95], v[122:123], v[98:99]
	v_pk_fma_f32 v[124:125], v[96:97], v[124:125], v[100:101]
	v_pk_mul_f32 v[128:129], v[120:121], v[128:129] op_sel:[1,0]
	v_pk_mul_f32 v[126:127], v[120:121], v[126:127] op_sel:[1,0]
	v_pk_fma_f32 v[128:129], v[88:89], v[128:129], v[92:93]
	v_pk_fma_f32 v[126:127], v[86:87], v[126:127], v[90:91]
	v_pk_fma_f32 v[116:117], v[124:125], s[18:19], v[116:117] op_sel_hi:[1,0,1]
	v_pk_fma_f32 v[114:115], v[122:123], s[18:19], v[114:115] op_sel_hi:[1,0,1]
	v_pk_fma_f32 v[122:123], v[128:129], s[18:19], v[112:113] op_sel_hi:[1,0,1]
	v_pk_fma_f32 v[112:113], v[126:127], s[18:19], v[110:111] op_sel_hi:[1,0,1]
	v_pk_mov_b32 v[110:111], v[114:115], v[116:117] op_sel:[1,0]
	v_mov_b32_e32 v124, v114
	v_mov_b32_e32 v125, v117
	v_pk_add_f32 v[124:125], v[110:111], v[124:125]
	v_pk_mul_f32 v[110:111], v[116:117], v[116:117]
	v_pk_mul_f32 v[128:129], v[114:115], v[114:115]
	v_lshlrev_b64 v[118:119], 10, v[206:207]
	v_pk_mov_b32 v[130:131], v[128:129], v[110:111] op_sel:[1,0]
	v_mov_b32_e32 v129, v111
	v_pk_add_f32 v[110:111], v[130:131], v[128:129]
	v_lshl_add_u64 v[118:119], v[118:119], 1, v[200:201]
	v_pk_add_f32 v[128:129], v[110:111], v[110:111] op_sel_hi:[0,1]
	v_mul_f32_e32 v110, v112, v112
	v_add_f32_e32 v126, v112, v113
	v_pk_fma_f32 v[130:131], v[112:113], v[112:113], v[110:111] op_sel_hi:[1,1,0]
	v_cvt_pk_f16_f32 v110, v114, v115
	v_cvt_pk_f16_f32 v111, v116, v117
	v_cvt_pk_f16_f32 v112, v112, v113
	v_cvt_pk_f16_f32 v113, v122, v123
	global_store_dwordx4 v[118:119], v[110:113], off
	v_cvt_f32_f16_e32 v114, v159
	v_cvt_f32_f16_sdwa v115, v160 dst_sel:DWORD dst_unused:UNUSED_PAD src0_sel:WORD_1
	v_cvt_f32_f16_sdwa v110, v158 dst_sel:DWORD dst_unused:UNUSED_PAD src0_sel:WORD_1
	v_cvt_f32_f16_e32 v112, v158
	v_cvt_f32_f16_sdwa v113, v159 dst_sel:DWORD dst_unused:UNUSED_PAD src0_sel:WORD_1
	v_cvt_f32_f16_e32 v116, v160
	v_cvt_f32_f16_sdwa v117, v161 dst_sel:DWORD dst_unused:UNUSED_PAD src0_sel:WORD_1
	v_cvt_f32_f16_e32 v127, v161
	v_sub_f32_e32 v111, v110, v120
	v_sub_f32_e32 v113, v113, v120
	v_sub_f32_e32 v110, v112, v120
	v_sub_f32_e32 v112, v114, v120
	v_pk_mul_f32 v[112:113], v[120:121], v[112:113] op_sel:[1,0]
	v_pk_mul_f32 v[110:111], v[120:121], v[110:111] op_sel:[1,0]
	v_sub_f32_e32 v115, v115, v120
	v_sub_f32_e32 v117, v117, v120
	v_sub_f32_e32 v114, v116, v120
	v_sub_f32_e32 v116, v127, v120
	v_pk_fma_f32 v[110:111], v[78:79], v[110:111], v[82:83]
	v_pk_fma_f32 v[112:113], v[80:81], v[112:113], v[84:85]
	v_pk_mul_f32 v[116:117], v[120:121], v[116:117] op_sel:[1,0]
	v_pk_mul_f32 v[114:115], v[120:121], v[114:115] op_sel:[1,0]
	v_pk_fma_f32 v[116:117], v[68:69], v[116:117], v[72:73]
	v_pk_fma_f32 v[114:115], v[66:67], v[114:115], v[70:71]
	v_pk_fma_f32 v[108:109], v[112:113], s[18:19], v[108:109] op_sel_hi:[1,0,1]
	v_pk_fma_f32 v[106:107], v[110:111], s[18:19], v[106:107] op_sel_hi:[1,0,1]
	v_pk_fma_f32 v[110:111], v[116:117], s[18:19], v[104:105] op_sel_hi:[1,0,1]
	v_pk_fma_f32 v[104:105], v[114:115], s[18:19], v[102:103] op_sel_hi:[1,0,1]
	v_pk_mov_b32 v[102:103], v[106:107], v[108:109] op_sel:[1,0]
	v_mov_b32_e32 v112, v106
	v_mov_b32_e32 v113, v109
	v_pk_add_f32 v[112:113], v[102:103], v[112:113]
	v_mul_f32_e32 v102, v106, v106
	v_pk_fma_f32 v[114:115], v[106:107], v[106:107], v[102:103] op_sel_hi:[1,1,0]
	v_mul_f32_e32 v102, v108, v108
	v_pk_fma_f32 v[116:117], v[108:109], v[108:109], v[102:103] op_sel_hi:[1,1,0]
	v_mul_f32_e32 v102, v110, v110
	v_add_f32_e32 v132, v104, v105
	v_mul_f32_e32 v127, v104, v104
	v_mul_f32_e32 v134, v105, v105
	v_pk_fma_f32 v[120:121], v[110:111], v[110:111], v[102:103] op_sel_hi:[1,1,0]
	v_cvt_pk_f16_f32 v102, v106, v107
	v_cvt_pk_f16_f32 v103, v108, v109
	v_cvt_pk_f16_f32 v104, v104, v105
	v_cvt_pk_f16_f32 v105, v110, v111
	v_mul_f32_e32 v1, v123, v123
	global_store_dwordx4 v[118:119], v[102:105], off offset:256
	v_mul_f32_e32 v133, v122, v122
	v_mov_b32_e32 v130, v110
	v_pk_add_f32 v[102:103], v[112:113], v[112:113] op_sel:[0,1] op_sel_hi:[1,0]
	v_mov_b32_e32 v128, v111
	v_mov_b32_e32 v103, v1
	v_pk_add_f32 v[106:107], v[124:125], v[124:125] op_sel:[0,1] op_sel_hi:[1,0]
	v_pk_add_f32 v[102:103], v[132:133], v[102:103]
	v_pk_add_f32 v[104:105], v[130:131], v[128:129]
	v_mov_b32_e32 v114, v122
	v_mov_b32_e32 v116, v123
	v_mov_b32_e32 v107, v134
	v_pk_add_f32 v[102:103], v[102:103], v[104:105]
	v_pk_add_f32 v[104:105], v[114:115], v[116:117]
	v_pk_add_f32 v[106:107], v[126:127], v[106:107]
	v_mov_b32_e32 v1, v121
	v_pk_add_f32 v[104:105], v[106:107], v[104:105]
	s_nop 0
	v_pk_add_f32 v[104:105], v[104:105], v[0:1]
	s_nop 0
	v_pk_add_f32 v[102:103], v[102:103], v[104:105]
	ds_bpermute_b32 v104, v227, v102
	ds_bpermute_b32 v105, v227, v103
	s_waitcnt lgkmcnt(0)
	v_pk_add_f32 v[102:103], v[102:103], v[104:105]
	ds_bpermute_b32 v104, v226, v102
	ds_bpermute_b32 v105, v226, v103
	s_and_saveexec_b64 s[22:23], s[36:37]
	s_cbranch_execz .LBB0_1145
	s_waitcnt lgkmcnt(0)
	v_pk_add_f32 v[102:103], v[102:103], v[104:105]
	v_lshlrev_b64 v[104:105], 7, v[206:207]
	v_lshl_add_u64 v[104:105], s[44:45], 0, v[104:105]
	v_lshl_add_u64 v[104:105], vcc, 3, v[104:105]
	s_lshl_b32 s58, s71, 3
	v_lshl_add_u64 v[104:105], v[104:105], 0, s[58:59]
	global_store_dwordx2 v[104:105], v[102:103], off
